# hand 16x16x32 GEMM loop also at the out-projection site; LDS-DMA issue split in two groups of four per k-tile (operand A group after the first 16 MFMAs, operand B group at tile top)
# speedup vs baseline: 1.2469x; 1.0317x over previous
; #define MFMA32(a, b, c) __builtin_amdgcn_mfma_f32_32x32x16_bf16((a), (b), (c), 0, 0, 0)
; DI void gemm256(const char* a_u, unsigned a_voff, size_t astep, const char* b_u, unsigned b_voff, size_t bstep, int nk, char* smem, f32x16 (&acc)[4][2]) {
;     ...
;   for (int kt = 0; kt < nk; ++kt) {
;     const int cur = kt & 1, k2 = (kt + 2 < last) ? kt + 2 : last;
;     const char* S = smem + cur * 2 * T2;
;     char* D = smem + (cur ^ 1) * 2 * T2;
;     const char* an = a_u + (size_t)k2 * 128;
;     const char* bn = b_u + (size_t)k2 * 128;
; #pragma unroll
;     for (int s = 0; s < 4; ++s) {
;       bf16x8 a[4], b[2];
; #pragma unroll
;       for (int mi = 0; mi < 4; ++mi) a[mi] = *(const bf16x8*)(S + aoff + mi * 32 * LROW + s * 32);
; #pragma unroll
;       for (int ni = 0; ni < 2; ++ni) b[ni] = *(const bf16x8*)(S + boff + ni * 32 * LROW + s * 32);
;       *(u32x4*)(D + soff + s * 64 * LROW) = ra[s];
;       *(u32x4*)(D + T2 + soff + s * 64 * LROW) = rb[s];
;       ra[s] = *(const u32x4*)(an + s * astep + a_voff);
;       rb[s] = *(const u32x4*)(bn + s * bstep + b_voff);
; #pragma unroll
;       for (int mi = 0; mi < 4; ++mi)
; #pragma unroll
;         for (int ni = 0; ni < 2; ++ni) acc[mi][ni] = MFMA32(a[mi], b[ni], acc[mi][ni]);
;     }
;     __syncthreads();
;   }
.Lg_inproj_loop:
	s_add_i32 s56, s56, 1
	s_add_u32 m0, s59, 0x8000
	s_nop 0
	global_load_lds_dwordx4 v164, s[54:55]
	s_add_u32 m0, s59, 0x8400
	s_nop 0
	global_load_lds_dwordx4 v165, s[54:55]
	s_add_u32 m0, s59, 0x8800
	s_nop 0
	global_load_lds_dwordx4 v130, s[54:55]
	s_add_u32 m0, s59, 0x8c00
	s_nop 0
	global_load_lds_dwordx4 v131, s[54:55]
	s_waitcnt lgkmcnt(0)
	v_mfma_f32_16x16x32_bf16 v[114:117], v[196:199], v[212:215], v[114:117]
	ds_read_b128 v[220:223], v194 offset:2048
	v_mfma_f32_16x16x32_bf16 v[118:121], v[196:199], v[216:219], v[118:121]
	ds_read_b128 v[224:227], v194 offset:6144
	v_mfma_f32_16x16x32_bf16 v[50:53], v[196:199], v[242:245], v[50:53]
	ds_read_b128 v[228:231], v194 offset:10240
	v_mfma_f32_16x16x32_bf16 v[54:57], v[196:199], v[246:249], v[54:57]
	ds_read_b128 v[238:241], v194 offset:14336
	v_mfma_f32_16x16x32_bf16 v[98:101], v[200:203], v[212:215], v[98:101]
	v_mfma_f32_16x16x32_bf16 v[102:105], v[200:203], v[216:219], v[102:105]
	v_mfma_f32_16x16x32_bf16 v[34:37], v[200:203], v[242:245], v[34:37]
	v_mfma_f32_16x16x32_bf16 v[38:41], v[200:203], v[246:249], v[38:41]
	v_mfma_f32_16x16x32_bf16 v[82:85], v[204:207], v[212:215], v[82:85]
	v_mfma_f32_16x16x32_bf16 v[86:89], v[204:207], v[216:219], v[86:89]
	v_mfma_f32_16x16x32_bf16 v[18:21], v[204:207], v[242:245], v[18:21]
	v_mfma_f32_16x16x32_bf16 v[22:25], v[204:207], v[246:249], v[22:25]
	v_mfma_f32_16x16x32_bf16 v[66:69], v[208:211], v[212:215], v[66:69]
	v_mfma_f32_16x16x32_bf16 v[70:73], v[208:211], v[216:219], v[70:73]
	v_mfma_f32_16x16x32_bf16 v[2:5], v[208:211], v[242:245], v[2:5]
	v_mfma_f32_16x16x32_bf16 v[6:9], v[208:211], v[246:249], v[6:9]
	s_add_u32 m0, s58, 0x8000
	s_nop 0
	global_load_lds_dwordx4 v164, s[52:53]
	s_add_u32 m0, s58, 0x8400
	s_nop 0
	global_load_lds_dwordx4 v165, s[52:53]
	s_add_u32 m0, s58, 0x8800
	s_nop 0
	global_load_lds_dwordx4 v130, s[52:53]
	s_add_u32 m0, s58, 0x8c00
	s_nop 0
	global_load_lds_dwordx4 v131, s[52:53]
	s_waitcnt lgkmcnt(0)
	v_mfma_f32_16x16x32_bf16 v[122:125], v[220:223], v[212:215], v[122:125]
	ds_read_b128 v[196:199], v195 offset:0
	v_mfma_f32_16x16x32_bf16 v[126:129], v[220:223], v[216:219], v[126:129]
	ds_read_b128 v[140:143], v161 offset:0
	v_mfma_f32_16x16x32_bf16 v[58:61], v[220:223], v[242:245], v[58:61]
	ds_read_b128 v[144:147], v161 offset:2048
	v_mfma_f32_16x16x32_bf16 v[62:65], v[220:223], v[246:249], v[62:65]
	ds_read_b128 v[148:151], v161 offset:4096
	v_mfma_f32_16x16x32_bf16 v[106:109], v[224:227], v[212:215], v[106:109]
	ds_read_b128 v[152:155], v161 offset:6144
	v_mfma_f32_16x16x32_bf16 v[110:113], v[224:227], v[216:219], v[110:113]
	ds_read_b128 v[200:203], v195 offset:4096
	v_mfma_f32_16x16x32_bf16 v[42:45], v[224:227], v[242:245], v[42:45]
	ds_read_b128 v[204:207], v195 offset:8192
	v_mfma_f32_16x16x32_bf16 v[46:49], v[224:227], v[246:249], v[46:49]
	ds_read_b128 v[208:211], v195 offset:12288
	v_mfma_f32_16x16x32_bf16 v[90:93], v[228:231], v[212:215], v[90:93]
	v_mfma_f32_16x16x32_bf16 v[94:97], v[228:231], v[216:219], v[94:97]
	v_mfma_f32_16x16x32_bf16 v[26:29], v[228:231], v[242:245], v[26:29]
	v_mfma_f32_16x16x32_bf16 v[30:33], v[228:231], v[246:249], v[30:33]
	v_mfma_f32_16x16x32_bf16 v[74:77], v[238:241], v[212:215], v[74:77]
	v_mfma_f32_16x16x32_bf16 v[78:81], v[238:241], v[216:219], v[78:81]
	v_mfma_f32_16x16x32_bf16 v[10:13], v[238:241], v[242:245], v[10:13]
	v_mfma_f32_16x16x32_bf16 v[14:17], v[238:241], v[246:249], v[14:17]
	s_waitcnt lgkmcnt(0)
	v_mfma_f32_16x16x32_bf16 v[114:117], v[196:199], v[140:143], v[114:117]
	ds_read_b128 v[220:223], v195 offset:2048
	v_mfma_f32_16x16x32_bf16 v[118:121], v[196:199], v[144:147], v[118:121]
	ds_read_b128 v[224:227], v195 offset:6144
	v_mfma_f32_16x16x32_bf16 v[50:53], v[196:199], v[148:151], v[50:53]
	ds_read_b128 v[228:231], v195 offset:10240
	v_mfma_f32_16x16x32_bf16 v[54:57], v[196:199], v[152:155], v[54:57]
	ds_read_b128 v[238:241], v195 offset:14336
	v_mfma_f32_16x16x32_bf16 v[98:101], v[200:203], v[140:143], v[98:101]
	v_mfma_f32_16x16x32_bf16 v[102:105], v[200:203], v[144:147], v[102:105]
	v_mfma_f32_16x16x32_bf16 v[34:37], v[200:203], v[148:151], v[34:37]
	v_mfma_f32_16x16x32_bf16 v[38:41], v[200:203], v[152:155], v[38:41]
	v_mfma_f32_16x16x32_bf16 v[82:85], v[204:207], v[140:143], v[82:85]
	v_mfma_f32_16x16x32_bf16 v[86:89], v[204:207], v[144:147], v[86:89]
	s_cmp_lt_u32 s56, s57
	s_cselect_b32 s60, 0x80, 0
	s_add_u32 s52, s52, s60
	s_addc_u32 s53, s53, 0
	s_add_u32 s54, s54, s60
	s_addc_u32 s55, s55, 0
	s_cmp_eq_u32 s56, s63
	s_cselect_b32 s52, s64, s52
	s_cselect_b32 s53, s65, s53
	s_cselect_b32 s54, s66, s54
	s_cselect_b32 s55, s67, s55
	v_mfma_f32_16x16x32_bf16 v[18:21], v[204:207], v[148:151], v[18:21]
	v_mfma_f32_16x16x32_bf16 v[22:25], v[204:207], v[152:155], v[22:25]
	v_mfma_f32_16x16x32_bf16 v[66:69], v[208:211], v[140:143], v[66:69]
	v_mfma_f32_16x16x32_bf16 v[70:73], v[208:211], v[144:147], v[70:73]
	v_mfma_f32_16x16x32_bf16 v[2:5], v[208:211], v[148:151], v[2:5]
	v_mfma_f32_16x16x32_bf16 v[6:9], v[208:211], v[152:155], v[6:9]
	s_waitcnt lgkmcnt(0)
	v_mfma_f32_16x16x32_bf16 v[122:125], v[220:223], v[140:143], v[122:125]
	v_mfma_f32_16x16x32_bf16 v[126:129], v[220:223], v[144:147], v[126:129]
	v_mfma_f32_16x16x32_bf16 v[58:61], v[220:223], v[148:151], v[58:61]
	v_mfma_f32_16x16x32_bf16 v[62:65], v[220:223], v[152:155], v[62:65]
	v_mfma_f32_16x16x32_bf16 v[106:109], v[224:227], v[140:143], v[106:109]
	v_mfma_f32_16x16x32_bf16 v[110:113], v[224:227], v[144:147], v[110:113]
	v_mfma_f32_16x16x32_bf16 v[42:45], v[224:227], v[148:151], v[42:45]
	v_mfma_f32_16x16x32_bf16 v[46:49], v[224:227], v[152:155], v[46:49]
	v_mfma_f32_16x16x32_bf16 v[90:93], v[228:231], v[140:143], v[90:93]
	v_mfma_f32_16x16x32_bf16 v[94:97], v[228:231], v[144:147], v[94:97]
	v_mfma_f32_16x16x32_bf16 v[26:29], v[228:231], v[148:151], v[26:29]
	v_mfma_f32_16x16x32_bf16 v[30:33], v[228:231], v[152:155], v[30:33]
	v_mfma_f32_16x16x32_bf16 v[74:77], v[238:241], v[140:143], v[74:77]
	v_mfma_f32_16x16x32_bf16 v[78:81], v[238:241], v[144:147], v[78:81]
	v_mfma_f32_16x16x32_bf16 v[10:13], v[238:241], v[148:151], v[10:13]
	v_mfma_f32_16x16x32_bf16 v[14:17], v[238:241], v[152:155], v[14:17]
	s_waitcnt vmcnt(0)
	s_barrier
; #define MFMA32(a, b, c) __builtin_amdgcn_mfma_f32_32x32x16_bf16((a), (b), (c), 0, 0, 0)
; DI void gemm256(const char* a_u, unsigned a_voff, size_t astep, const char* b_u, unsigned b_voff, size_t bstep, int nk, char* smem, f32x16 (&acc)[4][2]) {
;     ...
;   for (int kt = 0; kt < nk; ++kt) {
;     const int cur = kt & 1, k2 = (kt + 2 < last) ? kt + 2 : last;
;     const char* S = smem + cur * 2 * T2;
;     char* D = smem + (cur ^ 1) * 2 * T2;
;     const char* an = a_u + (size_t)k2 * 128;
;     const char* bn = b_u + (size_t)k2 * 128;
; #pragma unroll
;     for (int s = 0; s < 4; ++s) {
;       bf16x8 a[4], b[2];
; #pragma unroll
;       for (int mi = 0; mi < 4; ++mi) a[mi] = *(const bf16x8*)(S + aoff + mi * 32 * LROW + s * 32);
; #pragma unroll
;       for (int ni = 0; ni < 2; ++ni) b[ni] = *(const bf16x8*)(S + boff + ni * 32 * LROW + s * 32);
;       *(u32x4*)(D + soff + s * 64 * LROW) = ra[s];
;       *(u32x4*)(D + T2 + soff + s * 64 * LROW) = rb[s];
;       ra[s] = *(const u32x4*)(an + s * astep + a_voff);
;       rb[s] = *(const u32x4*)(bn + s * bstep + b_voff);
; #pragma unroll
;       for (int mi = 0; mi < 4; ++mi)
; #pragma unroll
;         for (int ni = 0; ni < 2; ++ni) acc[mi][ni] = MFMA32(a[mi], b[ni], acc[mi][ni]);
;     }
;     __syncthreads();
;   }
	ds_read_b128 v[196:199], v194 offset:32768
	ds_read_b128 v[212:215], v160 offset:32768
	ds_read_b128 v[216:219], v160 offset:34816
	ds_read_b128 v[242:245], v160 offset:36864
	ds_read_b128 v[246:249], v160 offset:38912
	ds_read_b128 v[200:203], v194 offset:36864
	ds_read_b128 v[204:207], v194 offset:40960
	ds_read_b128 v[208:211], v194 offset:45056
	s_add_i32 s56, s56, 1
	s_add_u32 m0, s59, 0x0
	s_nop 0
	global_load_lds_dwordx4 v164, s[54:55]
	s_add_u32 m0, s59, 0x400
	s_nop 0
	global_load_lds_dwordx4 v165, s[54:55]
	s_add_u32 m0, s59, 0x800
	s_nop 0
	global_load_lds_dwordx4 v130, s[54:55]
	s_add_u32 m0, s59, 0xc00
	s_nop 0
	global_load_lds_dwordx4 v131, s[54:55]
	s_waitcnt lgkmcnt(0)
	v_mfma_f32_16x16x32_bf16 v[114:117], v[196:199], v[212:215], v[114:117]
	ds_read_b128 v[220:223], v194 offset:34816
	v_mfma_f32_16x16x32_bf16 v[118:121], v[196:199], v[216:219], v[118:121]
	ds_read_b128 v[224:227], v194 offset:38912
	v_mfma_f32_16x16x32_bf16 v[50:53], v[196:199], v[242:245], v[50:53]
	ds_read_b128 v[228:231], v194 offset:43008
	v_mfma_f32_16x16x32_bf16 v[54:57], v[196:199], v[246:249], v[54:57]
	ds_read_b128 v[238:241], v194 offset:47104
	v_mfma_f32_16x16x32_bf16 v[98:101], v[200:203], v[212:215], v[98:101]
	v_mfma_f32_16x16x32_bf16 v[102:105], v[200:203], v[216:219], v[102:105]
	v_mfma_f32_16x16x32_bf16 v[34:37], v[200:203], v[242:245], v[34:37]
	v_mfma_f32_16x16x32_bf16 v[38:41], v[200:203], v[246:249], v[38:41]
	v_mfma_f32_16x16x32_bf16 v[82:85], v[204:207], v[212:215], v[82:85]
	v_mfma_f32_16x16x32_bf16 v[86:89], v[204:207], v[216:219], v[86:89]
	v_mfma_f32_16x16x32_bf16 v[18:21], v[204:207], v[242:245], v[18:21]
	v_mfma_f32_16x16x32_bf16 v[22:25], v[204:207], v[246:249], v[22:25]
	v_mfma_f32_16x16x32_bf16 v[66:69], v[208:211], v[212:215], v[66:69]
	v_mfma_f32_16x16x32_bf16 v[70:73], v[208:211], v[216:219], v[70:73]
	v_mfma_f32_16x16x32_bf16 v[2:5], v[208:211], v[242:245], v[2:5]
	v_mfma_f32_16x16x32_bf16 v[6:9], v[208:211], v[246:249], v[6:9]
	s_add_u32 m0, s58, 0x0
	s_nop 0
	global_load_lds_dwordx4 v164, s[52:53]
	s_add_u32 m0, s58, 0x400
	s_nop 0
	global_load_lds_dwordx4 v165, s[52:53]
	s_add_u32 m0, s58, 0x800
	s_nop 0
	global_load_lds_dwordx4 v130, s[52:53]
	s_add_u32 m0, s58, 0xc00
	s_nop 0
	global_load_lds_dwordx4 v131, s[52:53]
	s_waitcnt lgkmcnt(0)
	v_mfma_f32_16x16x32_bf16 v[122:125], v[220:223], v[212:215], v[122:125]
	ds_read_b128 v[196:199], v195 offset:32768
	v_mfma_f32_16x16x32_bf16 v[126:129], v[220:223], v[216:219], v[126:129]
	ds_read_b128 v[140:143], v161 offset:32768
	v_mfma_f32_16x16x32_bf16 v[58:61], v[220:223], v[242:245], v[58:61]
	ds_read_b128 v[144:147], v161 offset:34816
	v_mfma_f32_16x16x32_bf16 v[62:65], v[220:223], v[246:249], v[62:65]
	ds_read_b128 v[148:151], v161 offset:36864
	v_mfma_f32_16x16x32_bf16 v[106:109], v[224:227], v[212:215], v[106:109]
	ds_read_b128 v[152:155], v161 offset:38912
	v_mfma_f32_16x16x32_bf16 v[110:113], v[224:227], v[216:219], v[110:113]
	ds_read_b128 v[200:203], v195 offset:36864
	v_mfma_f32_16x16x32_bf16 v[42:45], v[224:227], v[242:245], v[42:45]
	ds_read_b128 v[204:207], v195 offset:40960
	v_mfma_f32_16x16x32_bf16 v[46:49], v[224:227], v[246:249], v[46:49]
	ds_read_b128 v[208:211], v195 offset:45056
	v_mfma_f32_16x16x32_bf16 v[90:93], v[228:231], v[212:215], v[90:93]
	v_mfma_f32_16x16x32_bf16 v[94:97], v[228:231], v[216:219], v[94:97]
	v_mfma_f32_16x16x32_bf16 v[26:29], v[228:231], v[242:245], v[26:29]
	v_mfma_f32_16x16x32_bf16 v[30:33], v[228:231], v[246:249], v[30:33]
	v_mfma_f32_16x16x32_bf16 v[74:77], v[238:241], v[212:215], v[74:77]
	v_mfma_f32_16x16x32_bf16 v[78:81], v[238:241], v[216:219], v[78:81]
	v_mfma_f32_16x16x32_bf16 v[10:13], v[238:241], v[242:245], v[10:13]
	v_mfma_f32_16x16x32_bf16 v[14:17], v[238:241], v[246:249], v[14:17]
	s_waitcnt lgkmcnt(0)
	v_mfma_f32_16x16x32_bf16 v[114:117], v[196:199], v[140:143], v[114:117]
	ds_read_b128 v[220:223], v195 offset:34816
	v_mfma_f32_16x16x32_bf16 v[118:121], v[196:199], v[144:147], v[118:121]
	ds_read_b128 v[224:227], v195 offset:38912
	v_mfma_f32_16x16x32_bf16 v[50:53], v[196:199], v[148:151], v[50:53]
	ds_read_b128 v[228:231], v195 offset:43008
	v_mfma_f32_16x16x32_bf16 v[54:57], v[196:199], v[152:155], v[54:57]
	ds_read_b128 v[238:241], v195 offset:47104
	v_mfma_f32_16x16x32_bf16 v[98:101], v[200:203], v[140:143], v[98:101]
	v_mfma_f32_16x16x32_bf16 v[102:105], v[200:203], v[144:147], v[102:105]
	v_mfma_f32_16x16x32_bf16 v[34:37], v[200:203], v[148:151], v[34:37]
	v_mfma_f32_16x16x32_bf16 v[38:41], v[200:203], v[152:155], v[38:41]
	v_mfma_f32_16x16x32_bf16 v[82:85], v[204:207], v[140:143], v[82:85]
	v_mfma_f32_16x16x32_bf16 v[86:89], v[204:207], v[144:147], v[86:89]
	s_cmp_lt_u32 s56, s57
	s_cselect_b32 s60, 0x80, 0
	s_add_u32 s52, s52, s60
	s_addc_u32 s53, s53, 0
	s_add_u32 s54, s54, s60
	s_addc_u32 s55, s55, 0
	s_cmp_eq_u32 s56, s63
	s_cselect_b32 s52, s64, s52
	s_cselect_b32 s53, s65, s53
	s_cselect_b32 s54, s66, s54
	s_cselect_b32 s55, s67, s55
	v_mfma_f32_16x16x32_bf16 v[18:21], v[204:207], v[148:151], v[18:21]
	v_mfma_f32_16x16x32_bf16 v[22:25], v[204:207], v[152:155], v[22:25]
	v_mfma_f32_16x16x32_bf16 v[66:69], v[208:211], v[140:143], v[66:69]
	v_mfma_f32_16x16x32_bf16 v[70:73], v[208:211], v[144:147], v[70:73]
	v_mfma_f32_16x16x32_bf16 v[2:5], v[208:211], v[148:151], v[2:5]
	v_mfma_f32_16x16x32_bf16 v[6:9], v[208:211], v[152:155], v[6:9]
	s_waitcnt lgkmcnt(0)
	v_mfma_f32_16x16x32_bf16 v[122:125], v[220:223], v[140:143], v[122:125]
	v_mfma_f32_16x16x32_bf16 v[126:129], v[220:223], v[144:147], v[126:129]
	v_mfma_f32_16x16x32_bf16 v[58:61], v[220:223], v[148:151], v[58:61]
	v_mfma_f32_16x16x32_bf16 v[62:65], v[220:223], v[152:155], v[62:65]
	v_mfma_f32_16x16x32_bf16 v[106:109], v[224:227], v[140:143], v[106:109]
	v_mfma_f32_16x16x32_bf16 v[110:113], v[224:227], v[144:147], v[110:113]
	v_mfma_f32_16x16x32_bf16 v[42:45], v[224:227], v[148:151], v[42:45]
	v_mfma_f32_16x16x32_bf16 v[46:49], v[224:227], v[152:155], v[46:49]
	v_mfma_f32_16x16x32_bf16 v[90:93], v[228:231], v[140:143], v[90:93]
	v_mfma_f32_16x16x32_bf16 v[94:97], v[228:231], v[144:147], v[94:97]
	v_mfma_f32_16x16x32_bf16 v[26:29], v[228:231], v[148:151], v[26:29]
	v_mfma_f32_16x16x32_bf16 v[30:33], v[228:231], v[152:155], v[30:33]
	v_mfma_f32_16x16x32_bf16 v[74:77], v[238:241], v[140:143], v[74:77]
	v_mfma_f32_16x16x32_bf16 v[78:81], v[238:241], v[144:147], v[78:81]
	v_mfma_f32_16x16x32_bf16 v[10:13], v[238:241], v[148:151], v[10:13]
	v_mfma_f32_16x16x32_bf16 v[14:17], v[238:241], v[152:155], v[14:17]
	s_waitcnt vmcnt(0)
	s_barrier
; #define MFMA32(a, b, c) __builtin_amdgcn_mfma_f32_32x32x16_bf16((a), (b), (c), 0, 0, 0)
; DI void gemm256(const char* a_u, unsigned a_voff, size_t astep, const char* b_u, unsigned b_voff, size_t bstep, int nk, char* smem, f32x16 (&acc)[4][2]) {
;     ...
;   for (int kt = 0; kt < nk; ++kt) {
;     const int cur = kt & 1, k2 = (kt + 2 < last) ? kt + 2 : last;
;     const char* S = smem + cur * 2 * T2;
;     char* D = smem + (cur ^ 1) * 2 * T2;
;     const char* an = a_u + (size_t)k2 * 128;
;     const char* bn = b_u + (size_t)k2 * 128;
; #pragma unroll
;     for (int s = 0; s < 4; ++s) {
;       bf16x8 a[4], b[2];
; #pragma unroll
;       for (int mi = 0; mi < 4; ++mi) a[mi] = *(const bf16x8*)(S + aoff + mi * 32 * LROW + s * 32);
; #pragma unroll
;       for (int ni = 0; ni < 2; ++ni) b[ni] = *(const bf16x8*)(S + boff + ni * 32 * LROW + s * 32);
;       *(u32x4*)(D + soff + s * 64 * LROW) = ra[s];
;       *(u32x4*)(D + T2 + soff + s * 64 * LROW) = rb[s];
;       ra[s] = *(const u32x4*)(an + s * astep + a_voff);
;       rb[s] = *(const u32x4*)(bn + s * bstep + b_voff);
; #pragma unroll
;       for (int mi = 0; mi < 4; ++mi)
; #pragma unroll
;         for (int ni = 0; ni < 2; ++ni) acc[mi][ni] = MFMA32(a[mi], b[ni], acc[mi][ni]);
;     }
;     __syncthreads();
;   }
	ds_read_b128 v[196:199], v194 offset:0
	ds_read_b128 v[212:215], v160 offset:0
	ds_read_b128 v[216:219], v160 offset:2048
	ds_read_b128 v[242:245], v160 offset:4096
	ds_read_b128 v[246:249], v160 offset:6144
	ds_read_b128 v[200:203], v194 offset:4096
	ds_read_b128 v[204:207], v194 offset:8192
	ds_read_b128 v[208:211], v194 offset:12288
	s_cmp_lt_u32 s56, s57
	s_cbranch_scc1 .Lg_inproj_loop
	s_waitcnt vmcnt(0) lgkmcnt(0)
	s_nop 7
	s_nop 7
	v_permlane16_swap_b32_e32 v114, v118
	v_permlane16_swap_b32_e32 v115, v119
	v_permlane16_swap_b32_e32 v116, v120
	v_permlane16_swap_b32_e32 v117, v121
	v_permlane16_swap_b32_e32 v122, v126
	v_permlane16_swap_b32_e32 v123, v127
	v_permlane16_swap_b32_e32 v124, v128
	v_permlane16_swap_b32_e32 v125, v129
	v_permlane16_swap_b32_e32 v50, v54
	v_permlane16_swap_b32_e32 v51, v55
	v_permlane16_swap_b32_e32 v52, v56
	v_permlane16_swap_b32_e32 v53, v57
	v_permlane16_swap_b32_e32 v58, v62
	v_permlane16_swap_b32_e32 v59, v63
	v_permlane16_swap_b32_e32 v60, v64
	v_permlane16_swap_b32_e32 v61, v65
	v_permlane16_swap_b32_e32 v98, v102
	v_permlane16_swap_b32_e32 v99, v103
	v_permlane16_swap_b32_e32 v100, v104
	v_permlane16_swap_b32_e32 v101, v105
	v_permlane16_swap_b32_e32 v106, v110
	v_permlane16_swap_b32_e32 v107, v111
	v_permlane16_swap_b32_e32 v108, v112
	v_permlane16_swap_b32_e32 v109, v113
	v_permlane16_swap_b32_e32 v34, v38
	v_permlane16_swap_b32_e32 v35, v39
	v_permlane16_swap_b32_e32 v36, v40
	v_permlane16_swap_b32_e32 v37, v41
	v_permlane16_swap_b32_e32 v42, v46
	v_permlane16_swap_b32_e32 v43, v47
	v_permlane16_swap_b32_e32 v44, v48
	v_permlane16_swap_b32_e32 v45, v49
	v_permlane16_swap_b32_e32 v82, v86
	v_permlane16_swap_b32_e32 v83, v87
	v_permlane16_swap_b32_e32 v84, v88
	v_permlane16_swap_b32_e32 v85, v89
	v_permlane16_swap_b32_e32 v90, v94
	v_permlane16_swap_b32_e32 v91, v95
	v_permlane16_swap_b32_e32 v92, v96
	v_permlane16_swap_b32_e32 v93, v97
	v_permlane16_swap_b32_e32 v18, v22
	v_permlane16_swap_b32_e32 v19, v23
	v_permlane16_swap_b32_e32 v20, v24
	v_permlane16_swap_b32_e32 v21, v25
	v_permlane16_swap_b32_e32 v26, v30
	v_permlane16_swap_b32_e32 v27, v31
	v_permlane16_swap_b32_e32 v28, v32
	v_permlane16_swap_b32_e32 v29, v33
	v_permlane16_swap_b32_e32 v66, v70
	v_permlane16_swap_b32_e32 v67, v71
	v_permlane16_swap_b32_e32 v68, v72
	v_permlane16_swap_b32_e32 v69, v73
	v_permlane16_swap_b32_e32 v74, v78
	v_permlane16_swap_b32_e32 v75, v79
	v_permlane16_swap_b32_e32 v76, v80
	v_permlane16_swap_b32_e32 v77, v81
	v_permlane16_swap_b32_e32 v2, v6
	v_permlane16_swap_b32_e32 v3, v7
	v_permlane16_swap_b32_e32 v4, v8
	v_permlane16_swap_b32_e32 v5, v9
	v_permlane16_swap_b32_e32 v10, v14
	v_permlane16_swap_b32_e32 v11, v15
	v_permlane16_swap_b32_e32 v12, v16
	v_permlane16_swap_b32_e32 v13, v17
	v_permlane32_swap_b32_e32 v114, v118
	v_permlane32_swap_b32_e32 v115, v119
	v_permlane32_swap_b32_e32 v116, v120
	v_permlane32_swap_b32_e32 v117, v121
	v_permlane32_swap_b32_e32 v122, v126
	v_permlane32_swap_b32_e32 v123, v127
	v_permlane32_swap_b32_e32 v124, v128
	v_permlane32_swap_b32_e32 v125, v129
	v_permlane32_swap_b32_e32 v50, v54
	v_permlane32_swap_b32_e32 v51, v55
	v_permlane32_swap_b32_e32 v52, v56
	v_permlane32_swap_b32_e32 v53, v57
	v_permlane32_swap_b32_e32 v58, v62
	v_permlane32_swap_b32_e32 v59, v63
	v_permlane32_swap_b32_e32 v60, v64
	v_permlane32_swap_b32_e32 v61, v65
	v_permlane32_swap_b32_e32 v98, v102
	v_permlane32_swap_b32_e32 v99, v103
	v_permlane32_swap_b32_e32 v100, v104
	v_permlane32_swap_b32_e32 v101, v105
	v_permlane32_swap_b32_e32 v106, v110
	v_permlane32_swap_b32_e32 v107, v111
	v_permlane32_swap_b32_e32 v108, v112
	v_permlane32_swap_b32_e32 v109, v113
	v_permlane32_swap_b32_e32 v34, v38
	v_permlane32_swap_b32_e32 v35, v39
	v_permlane32_swap_b32_e32 v36, v40
	v_permlane32_swap_b32_e32 v37, v41
	v_permlane32_swap_b32_e32 v42, v46
	v_permlane32_swap_b32_e32 v43, v47
	v_permlane32_swap_b32_e32 v44, v48
	v_permlane32_swap_b32_e32 v45, v49
	v_permlane32_swap_b32_e32 v82, v86
	v_permlane32_swap_b32_e32 v83, v87
	v_permlane32_swap_b32_e32 v84, v88
	v_permlane32_swap_b32_e32 v85, v89
	v_permlane32_swap_b32_e32 v90, v94
	v_permlane32_swap_b32_e32 v91, v95
	v_permlane32_swap_b32_e32 v92, v96
	v_permlane32_swap_b32_e32 v93, v97
	v_permlane32_swap_b32_e32 v18, v22
	v_permlane32_swap_b32_e32 v19, v23
	v_permlane32_swap_b32_e32 v20, v24
	v_permlane32_swap_b32_e32 v21, v25
	v_permlane32_swap_b32_e32 v26, v30
	v_permlane32_swap_b32_e32 v27, v31
	v_permlane32_swap_b32_e32 v28, v32
	v_permlane32_swap_b32_e32 v29, v33
	v_permlane32_swap_b32_e32 v66, v70
	v_permlane32_swap_b32_e32 v67, v71
	v_permlane32_swap_b32_e32 v68, v72
	v_permlane32_swap_b32_e32 v69, v73
	v_permlane32_swap_b32_e32 v74, v78
	v_permlane32_swap_b32_e32 v75, v79
	v_permlane32_swap_b32_e32 v76, v80
	v_permlane32_swap_b32_e32 v77, v81
	v_permlane32_swap_b32_e32 v2, v6
	v_permlane32_swap_b32_e32 v3, v7
	v_permlane32_swap_b32_e32 v4, v8
	v_permlane32_swap_b32_e32 v5, v9
	v_permlane32_swap_b32_e32 v10, v14
	v_permlane32_swap_b32_e32 v11, v15
	v_permlane32_swap_b32_e32 v12, v16
	v_permlane32_swap_b32_e32 v13, v17
	s_nop 1
	s_branch .LBB0_195

; DI int tid512() { int t = threadIdx.x; asm volatile("" : "+v"(t)); return t; }
; DI unsigned voff256(size_t ld) { const int t = tid512(); return (unsigned)(((size_t)(t >> 3) * ld + (t & 7) * 8) * 2); }
; DI void gemm256(const char* a_u, unsigned a_voff, size_t astep, const char* b_u, unsigned b_voff, size_t bstep, int nk, char* smem, f32x16 (&acc)[4][2]) {
;   asm volatile("" : "+s"(nk));
;   const int t = tid512(), lane = t & 63, w = t >> 6, wm = w >> 2, wn = w & 3, r = lane & 31, h = lane >> 5;
;   const int soff = (t >> 3) * LROW + (t & 7) * 16;
;   const int aoff = (128 * wm + r) * LROW + h * 16, boff = T2 + (64 * wn + r) * LROW + h * 16;
;   u32x4 ra[4], rb[4];
; #pragma unroll
;   for (int i = 0; i < 4; ++i) { ra[i] = *(const u32x4*)(a_u + i * astep + a_voff); rb[i] = *(const u32x4*)(b_u + i * bstep + b_voff); }
;   __syncthreads();
; #pragma unroll
;   for (int i = 0; i < 4; ++i) { *(u32x4*)(smem + soff + i * 64 * LROW) = ra[i]; *(u32x4*)(smem + T2 + soff + i * 64 * LROW) = rb[i]; }
;   const int last = nk - 1;
;   {
;     const int k1 = last < 1 ? last : 1;
; #pragma unroll
;     for (int i = 0; i < 4; ++i) { ra[i] = *(const u32x4*)(a_u + i * astep + k1 * 128 + a_voff); rb[i] = *(const u32x4*)(b_u + i * bstep + k1 * 128 + b_voff); }
;   }
;   __syncthreads();
; DI void outproj256(const Params& p, int layer, char* smem) {
;     ...
;   for (int i = 0;; ++i) {
;     const int L = tile_of(i, 32 * 8);
;     if (L < 0) break;
;     int tm, tn; tile_mn(L, 32, 8, tm, tn);
;     f32x16 acc[4][2]; zero_acc256(acc);
;     gemm256((const char*)(Yb + (size_t)(256 + tm * 256) * DM), voff256(DM), (size_t)128 * DM, (const char*)(W + (size_t)(tn * 256) * DM), voff256(DM), (size_t)128 * DM, DM / 64, smem, acc);
.LBB0_918:
	s_lshr_b32 s4, s6, 3
	s_and_b32 s5, s4, 0xffffffc
	s_sub_i32 s4, 32, s5
	s_min_i32 s7, s4, 4
	s_abs_i32 s8, s7
	v_cvt_f32_u32_e32 v2, s8
	s_sub_i32 s9, 0, s8
	s_and_b32 s6, s6, 31
	s_ashr_i32 s4, s7, 31
	v_rcp_iflag_f32_e32 v2, v2
	v_mov_b32_e32 v37, v181
	v_mul_f32_e32 v2, 0x4f7ffffe, v2
	v_cvt_u32_f32_e32 v2, v2
	s_nop 0
	v_readfirstlane_b32 s13, v2
	s_mul_i32 s9, s9, s13
	s_mul_hi_u32 s9, s13, s9
	s_add_i32 s13, s13, s9
	s_mul_hi_u32 s9, s6, s13
	s_mul_i32 s13, s9, s8
	s_sub_i32 s13, s6, s13
	s_add_i32 s14, s9, 1
	s_sub_i32 s15, s13, s8
	s_cmp_ge_u32 s13, s8
	s_cselect_b32 s9, s14, s9
	s_cselect_b32 s13, s15, s13
	s_add_i32 s14, s9, 1
	s_cmp_ge_u32 s13, s8
	s_cselect_b32 s8, s14, s9
	s_xor_b32 s8, s8, s4
	s_sub_i32 s4, s8, s4
	s_mul_i32 s7, s4, s7
	s_sub_i32 s6, s6, s7
	s_add_i32 s6, s6, s5
	s_lshl_b32 s5, s6, 8
	s_add_i32 s22, s5, 0x100
	s_lshl_b64 s[6:7], s[22:23], 12
	v_readlane_b32 s5, v254, 20
	v_mov_b32_e32 v2, v0
	s_add_u32 s6, s5, s6
	v_readlane_b32 s5, v254, 21
	s_addc_u32 s7, s5, s7
	v_lshlrev_b32_e32 v3, 4, v2
	v_and_b32_e32 v3, 0x70, v3
	v_lshlrev_b32_e32 v2, 9, v2
	s_movk_i32 s13, 0xf000
	s_lshl_b32 s4, s4, 8
	v_and_or_b32 v180, v2, s13, v3
	s_ashr_i32 s5, s4, 31
	v_mov_b32_e32 v2, v0
	s_lshl_b64 s[8:9], s[4:5], 12
	s_add_u32 s8, s10, s8
	v_lshlrev_b32_e32 v3, 4, v2
	v_and_b32_e32 v3, 0x70, v3
	v_lshlrev_b32_e32 v2, 9, v2
	v_lshl_add_u64 v[162:163], s[6:7], 0, v[180:181]
	s_addc_u32 s9, s11, s9
	v_and_or_b32 v36, v2, s13, v3
	v_add_co_u32_e32 v12, vcc, s84, v162
	v_lshl_add_u64 v[164:165], s[8:9], 0, v[36:37]
	s_nop 0
	v_addc_co_u32_e32 v13, vcc, 0, v163, vcc
	v_add_co_u32_e32 v16, vcc, s84, v164
	s_mov_b32 s5, 32
	v_mov_b32_e32 v2, v0
	v_addc_co_u32_e32 v17, vcc, 0, v165, vcc
	v_add_co_u32_e32 v20, vcc, s31, v162
	v_lshlrev_b32_e32 v4, 4, v2
	v_and_b32_e32 v38, 0x70, v4
	v_lshrrev_b32_e32 v132, 6, v0
	s_nop 0
	v_readfirstlane_b32 s61, v132
	v_and_b32_e32 v132, 63, v0
	v_and_b32_e32 v133, 15, v132
	v_lshrrev_b32_e32 v136, 4, v132
	v_bfe_u32 v137, v133, 1, 3
	v_lshlrev_b32_e32 v133, 7, v133
	s_lshr_b32 s60, s61, 2
	s_lshl_b32 s60, s60, 14
	s_add_i32 s60, s60, 16
	s_and_b32 s62, s61, 3
	s_lshl_b32 s62, s62, 13
	s_add_i32 s62, s62, 0x10010
	v_add_u32_e32 v194, 0, v136
	v_xor_b32_e32 v194, v194, v137
	v_lshl_add_u32 v194, v194, 4, v133
	v_add_u32_e32 v160, s62, v194
	v_add_u32_e32 v194, s60, v194
	v_add_u32_e32 v195, 4, v136
	v_xor_b32_e32 v195, v195, v137
	v_lshl_add_u32 v195, v195, 4, v133
	v_add_u32_e32 v161, s62, v195
	v_add_u32_e32 v195, s60, v195
	v_lshrrev_b32_e32 v133, 3, v132
	s_mov_b32 s60, 0x1000
	v_mul_lo_u32 v133, v133, s60
	v_and_b32_e32 v136, 7, v132
	v_lshrrev_b32_e32 v137, 4, v132
	v_xor_b32_e32 v164, v137, v136
	v_lshl_add_u32 v164, v164, 4, v133
	v_add_u32_e32 v165, 4, v137
	v_xor_b32_e32 v165, v165, v136
	v_lshl_add_u32 v165, v165, 4, v133
	v_add_u32_e32 v165, 0x8000, v165
	v_xor_b32_e32 v130, v137, v136
	v_lshl_add_u32 v130, v130, 4, v133
	v_add_u32_e32 v130, 0x10000, v130
	v_add_u32_e32 v131, 4, v137
	v_xor_b32_e32 v131, v131, v136
	v_lshl_add_u32 v131, v131, 4, v133
	v_add_u32_e32 v131, 0x18000, v131
	s_mul_i32 s60, s61, 0x20000
	s_add_u32 s52, s6, s60
	s_addc_u32 s53, s7, 0
	s_add_u32 s54, s8, s60
	s_addc_u32 s55, s9, 0
	s_lshl_b32 s58, s61, 12
	s_add_i32 s58, s58, 16
	s_add_i32 s59, s58, 0x10000
	s_mov_b32 s56, 0
	s_mov_b32 s57, 31
	s_barrier
	s_add_u32 m0, s58, 0x0
	s_nop 0
	global_load_lds_dwordx4 v164, s[52:53]
	s_add_u32 m0, s58, 0x400
	s_nop 0
	global_load_lds_dwordx4 v165, s[52:53]
	s_add_u32 m0, s58, 0x800
	s_nop 0
	global_load_lds_dwordx4 v130, s[52:53]
	s_add_u32 m0, s58, 0xc00
	s_nop 0
	global_load_lds_dwordx4 v131, s[52:53]
	s_add_u32 m0, s59, 0x0
	s_nop 0
	global_load_lds_dwordx4 v164, s[54:55]
	s_add_u32 m0, s59, 0x400
	s_nop 0
	global_load_lds_dwordx4 v165, s[54:55]
	s_add_u32 m0, s59, 0x800
	s_nop 0
	global_load_lds_dwordx4 v130, s[54:55]
	s_add_u32 m0, s59, 0xc00
	s_nop 0
	global_load_lds_dwordx4 v131, s[54:55]
	s_cmp_lt_u32 s56, s57
	s_cselect_b32 s60, 0x80, 0
	s_add_u32 s52, s52, s60
	s_addc_u32 s53, s53, 0
	s_add_u32 s54, s54, s60
	s_addc_u32 s55, s55, 0
	v_mov_b64_e32 v[114:115], 0
	v_mov_b64_e32 v[116:117], 0
	v_mov_b64_e32 v[118:119], 0
	v_mov_b64_e32 v[120:121], 0
	v_mov_b64_e32 v[122:123], 0
	v_mov_b64_e32 v[124:125], 0
	v_mov_b64_e32 v[126:127], 0
	v_mov_b64_e32 v[128:129], 0
	v_mov_b64_e32 v[98:99], 0
	v_mov_b64_e32 v[100:101], 0
	v_mov_b64_e32 v[102:103], 0
	v_mov_b64_e32 v[104:105], 0
	v_mov_b64_e32 v[106:107], 0
	v_mov_b64_e32 v[108:109], 0
	v_mov_b64_e32 v[110:111], 0
	v_mov_b64_e32 v[112:113], 0
	v_mov_b64_e32 v[82:83], 0
	v_mov_b64_e32 v[84:85], 0
	v_mov_b64_e32 v[86:87], 0
	v_mov_b64_e32 v[88:89], 0
	v_mov_b64_e32 v[90:91], 0
	v_mov_b64_e32 v[92:93], 0
	v_mov_b64_e32 v[94:95], 0
	v_mov_b64_e32 v[96:97], 0
	v_mov_b64_e32 v[66:67], 0
	v_mov_b64_e32 v[68:69], 0
	v_mov_b64_e32 v[70:71], 0
	v_mov_b64_e32 v[72:73], 0
	v_mov_b64_e32 v[74:75], 0
	v_mov_b64_e32 v[76:77], 0
	v_mov_b64_e32 v[78:79], 0
	v_mov_b64_e32 v[80:81], 0
	v_mov_b64_e32 v[50:51], 0
	v_mov_b64_e32 v[52:53], 0
	v_mov_b64_e32 v[54:55], 0
	v_mov_b64_e32 v[56:57], 0
	v_mov_b64_e32 v[58:59], 0
	v_mov_b64_e32 v[60:61], 0
	v_mov_b64_e32 v[62:63], 0
	v_mov_b64_e32 v[64:65], 0
	v_mov_b64_e32 v[34:35], 0
	v_mov_b64_e32 v[36:37], 0
	v_mov_b64_e32 v[38:39], 0
	v_mov_b64_e32 v[40:41], 0
	v_mov_b64_e32 v[42:43], 0
	v_mov_b64_e32 v[44:45], 0
	v_mov_b64_e32 v[46:47], 0
	v_mov_b64_e32 v[48:49], 0
	v_mov_b64_e32 v[18:19], 0
	v_mov_b64_e32 v[20:21], 0
	v_mov_b64_e32 v[22:23], 0
	v_mov_b64_e32 v[24:25], 0
	v_mov_b64_e32 v[26:27], 0
	v_mov_b64_e32 v[28:29], 0
	v_mov_b64_e32 v[30:31], 0
	v_mov_b64_e32 v[32:33], 0
	v_mov_b64_e32 v[2:3], 0
	v_mov_b64_e32 v[4:5], 0
	v_mov_b64_e32 v[6:7], 0
	v_mov_b64_e32 v[8:9], 0
	v_mov_b64_e32 v[10:11], 0
	v_mov_b64_e32 v[12:13], 0
	v_mov_b64_e32 v[14:15], 0
	v_mov_b64_e32 v[16:17], 0
	s_waitcnt vmcnt(0)
	s_barrier
	ds_read_b128 v[196:199], v194 offset:0
	ds_read_b128 v[212:215], v160 offset:0
	ds_read_b128 v[216:219], v160 offset:2048
	ds_read_b128 v[242:245], v160 offset:4096
	ds_read_b128 v[246:249], v160 offset:6144
	ds_read_b128 v[200:203], v194 offset:4096
	ds_read_b128 v[204:207], v194 offset:8192
	ds_read_b128 v[208:211], v194 offset:12288
; #define MFMA32(a, b, c) __builtin_amdgcn_mfma_f32_32x32x16_bf16((a), (b), (c), 0, 0, 0)
; DI void gemm256(const char* a_u, unsigned a_voff, size_t astep, const char* b_u, unsigned b_voff, size_t bstep, int nk, char* smem, f32x16 (&acc)[4][2]) {
;     ...
;   for (int kt = 0; kt < nk; ++kt) {
;     const int cur = kt & 1, k2 = (kt + 2 < last) ? kt + 2 : last;
;     const char* S = smem + cur * 2 * T2;
;     char* D = smem + (cur ^ 1) * 2 * T2;
;     const char* an = a_u + (size_t)k2 * 128;
;     const char* bn = b_u + (size_t)k2 * 128;
; #pragma unroll
;     for (int s = 0; s < 4; ++s) {
;       bf16x8 a[4], b[2];
; #pragma unroll
;       for (int mi = 0; mi < 4; ++mi) a[mi] = *(const bf16x8*)(S + aoff + mi * 32 * LROW + s * 32);
; #pragma unroll
;       for (int ni = 0; ni < 2; ++ni) b[ni] = *(const bf16x8*)(S + boff + ni * 32 * LROW + s * 32);
;       *(u32x4*)(D + soff + s * 64 * LROW) = ra[s];
;       *(u32x4*)(D + T2 + soff + s * 64 * LROW) = rb[s];
;       ra[s] = *(const u32x4*)(an + s * astep + a_voff);
;       rb[s] = *(const u32x4*)(bn + s * bstep + b_voff);
; #pragma unroll
;       for (int mi = 0; mi < 4; ++mi)
; #pragma unroll
;         for (int ni = 0; ni < 2; ++ni) acc[mi][ni] = MFMA32(a[mi], b[ni], acc[mi][ni]);
;     }
;     __syncthreads();
;   }
.Lg_outproj_loop:
	s_add_i32 s56, s56, 1
	s_add_u32 m0, s59, 0x8000
	s_nop 0
	global_load_lds_dwordx4 v164, s[54:55]
	s_add_u32 m0, s59, 0x8400
	s_nop 0
	global_load_lds_dwordx4 v165, s[54:55]
	s_add_u32 m0, s59, 0x8800
	s_nop 0
	global_load_lds_dwordx4 v130, s[54:55]
	s_add_u32 m0, s59, 0x8c00
	s_nop 0
	global_load_lds_dwordx4 v131, s[54:55]
	s_waitcnt lgkmcnt(0)
	v_mfma_f32_16x16x32_bf16 v[114:117], v[196:199], v[212:215], v[114:117]
	ds_read_b128 v[220:223], v194 offset:2048
	v_mfma_f32_16x16x32_bf16 v[118:121], v[196:199], v[216:219], v[118:121]
	ds_read_b128 v[224:227], v194 offset:6144
	v_mfma_f32_16x16x32_bf16 v[98:101], v[196:199], v[242:245], v[98:101]
	ds_read_b128 v[228:231], v194 offset:10240
	v_mfma_f32_16x16x32_bf16 v[102:105], v[196:199], v[246:249], v[102:105]
	ds_read_b128 v[238:241], v194 offset:14336
	v_mfma_f32_16x16x32_bf16 v[82:85], v[200:203], v[212:215], v[82:85]
	v_mfma_f32_16x16x32_bf16 v[86:89], v[200:203], v[216:219], v[86:89]
	v_mfma_f32_16x16x32_bf16 v[66:69], v[200:203], v[242:245], v[66:69]
	v_mfma_f32_16x16x32_bf16 v[70:73], v[200:203], v[246:249], v[70:73]
	v_mfma_f32_16x16x32_bf16 v[50:53], v[204:207], v[212:215], v[50:53]
	v_mfma_f32_16x16x32_bf16 v[54:57], v[204:207], v[216:219], v[54:57]
	v_mfma_f32_16x16x32_bf16 v[34:37], v[204:207], v[242:245], v[34:37]
	v_mfma_f32_16x16x32_bf16 v[38:41], v[204:207], v[246:249], v[38:41]
	v_mfma_f32_16x16x32_bf16 v[18:21], v[208:211], v[212:215], v[18:21]
	v_mfma_f32_16x16x32_bf16 v[22:25], v[208:211], v[216:219], v[22:25]
	v_mfma_f32_16x16x32_bf16 v[2:5], v[208:211], v[242:245], v[2:5]
	v_mfma_f32_16x16x32_bf16 v[6:9], v[208:211], v[246:249], v[6:9]
	s_add_u32 m0, s58, 0x8000
	s_nop 0
	global_load_lds_dwordx4 v164, s[52:53]
	s_add_u32 m0, s58, 0x8400
	s_nop 0
	global_load_lds_dwordx4 v165, s[52:53]
	s_add_u32 m0, s58, 0x8800
	s_nop 0
	global_load_lds_dwordx4 v130, s[52:53]
	s_add_u32 m0, s58, 0x8c00
	s_nop 0
	global_load_lds_dwordx4 v131, s[52:53]
	s_waitcnt lgkmcnt(0)
	v_mfma_f32_16x16x32_bf16 v[122:125], v[220:223], v[212:215], v[122:125]
	ds_read_b128 v[196:199], v195 offset:0
	v_mfma_f32_16x16x32_bf16 v[126:129], v[220:223], v[216:219], v[126:129]
	ds_read_b128 v[140:143], v161 offset:0
	v_mfma_f32_16x16x32_bf16 v[106:109], v[220:223], v[242:245], v[106:109]
	ds_read_b128 v[144:147], v161 offset:2048
	v_mfma_f32_16x16x32_bf16 v[110:113], v[220:223], v[246:249], v[110:113]
	ds_read_b128 v[148:151], v161 offset:4096
	v_mfma_f32_16x16x32_bf16 v[90:93], v[224:227], v[212:215], v[90:93]
	ds_read_b128 v[152:155], v161 offset:6144
	v_mfma_f32_16x16x32_bf16 v[94:97], v[224:227], v[216:219], v[94:97]
	ds_read_b128 v[200:203], v195 offset:4096
	v_mfma_f32_16x16x32_bf16 v[74:77], v[224:227], v[242:245], v[74:77]
	ds_read_b128 v[204:207], v195 offset:8192
	v_mfma_f32_16x16x32_bf16 v[78:81], v[224:227], v[246:249], v[78:81]
	ds_read_b128 v[208:211], v195 offset:12288
	v_mfma_f32_16x16x32_bf16 v[58:61], v[228:231], v[212:215], v[58:61]
	v_mfma_f32_16x16x32_bf16 v[62:65], v[228:231], v[216:219], v[62:65]
	v_mfma_f32_16x16x32_bf16 v[42:45], v[228:231], v[242:245], v[42:45]
	v_mfma_f32_16x16x32_bf16 v[46:49], v[228:231], v[246:249], v[46:49]
	v_mfma_f32_16x16x32_bf16 v[26:29], v[238:241], v[212:215], v[26:29]
	v_mfma_f32_16x16x32_bf16 v[30:33], v[238:241], v[216:219], v[30:33]
	v_mfma_f32_16x16x32_bf16 v[10:13], v[238:241], v[242:245], v[10:13]
	v_mfma_f32_16x16x32_bf16 v[14:17], v[238:241], v[246:249], v[14:17]
	s_waitcnt lgkmcnt(0)
	v_mfma_f32_16x16x32_bf16 v[114:117], v[196:199], v[140:143], v[114:117]
	ds_read_b128 v[220:223], v195 offset:2048
	v_mfma_f32_16x16x32_bf16 v[118:121], v[196:199], v[144:147], v[118:121]
	ds_read_b128 v[224:227], v195 offset:6144
	v_mfma_f32_16x16x32_bf16 v[98:101], v[196:199], v[148:151], v[98:101]
	ds_read_b128 v[228:231], v195 offset:10240
	v_mfma_f32_16x16x32_bf16 v[102:105], v[196:199], v[152:155], v[102:105]
	ds_read_b128 v[238:241], v195 offset:14336
	v_mfma_f32_16x16x32_bf16 v[82:85], v[200:203], v[140:143], v[82:85]
	v_mfma_f32_16x16x32_bf16 v[86:89], v[200:203], v[144:147], v[86:89]
	v_mfma_f32_16x16x32_bf16 v[66:69], v[200:203], v[148:151], v[66:69]
	v_mfma_f32_16x16x32_bf16 v[70:73], v[200:203], v[152:155], v[70:73]
	v_mfma_f32_16x16x32_bf16 v[50:53], v[204:207], v[140:143], v[50:53]
	v_mfma_f32_16x16x32_bf16 v[54:57], v[204:207], v[144:147], v[54:57]
	s_cmp_lt_u32 s56, s57
	s_cselect_b32 s60, 0x80, 0
	s_add_u32 s52, s52, s60
	s_addc_u32 s53, s53, 0
	s_add_u32 s54, s54, s60
	s_addc_u32 s55, s55, 0
	v_mfma_f32_16x16x32_bf16 v[34:37], v[204:207], v[148:151], v[34:37]
	v_mfma_f32_16x16x32_bf16 v[38:41], v[204:207], v[152:155], v[38:41]
	v_mfma_f32_16x16x32_bf16 v[18:21], v[208:211], v[140:143], v[18:21]
	v_mfma_f32_16x16x32_bf16 v[22:25], v[208:211], v[144:147], v[22:25]
	v_mfma_f32_16x16x32_bf16 v[2:5], v[208:211], v[148:151], v[2:5]
	v_mfma_f32_16x16x32_bf16 v[6:9], v[208:211], v[152:155], v[6:9]
	s_waitcnt lgkmcnt(0)
	v_mfma_f32_16x16x32_bf16 v[122:125], v[220:223], v[140:143], v[122:125]
	v_mfma_f32_16x16x32_bf16 v[126:129], v[220:223], v[144:147], v[126:129]
	v_mfma_f32_16x16x32_bf16 v[106:109], v[220:223], v[148:151], v[106:109]
	v_mfma_f32_16x16x32_bf16 v[110:113], v[220:223], v[152:155], v[110:113]
	v_mfma_f32_16x16x32_bf16 v[90:93], v[224:227], v[140:143], v[90:93]
	v_mfma_f32_16x16x32_bf16 v[94:97], v[224:227], v[144:147], v[94:97]
	v_mfma_f32_16x16x32_bf16 v[74:77], v[224:227], v[148:151], v[74:77]
	v_mfma_f32_16x16x32_bf16 v[78:81], v[224:227], v[152:155], v[78:81]
	v_mfma_f32_16x16x32_bf16 v[58:61], v[228:231], v[140:143], v[58:61]
	v_mfma_f32_16x16x32_bf16 v[62:65], v[228:231], v[144:147], v[62:65]
	v_mfma_f32_16x16x32_bf16 v[42:45], v[228:231], v[148:151], v[42:45]
	v_mfma_f32_16x16x32_bf16 v[46:49], v[228:231], v[152:155], v[46:49]
	v_mfma_f32_16x16x32_bf16 v[26:29], v[238:241], v[140:143], v[26:29]
	v_mfma_f32_16x16x32_bf16 v[30:33], v[238:241], v[144:147], v[30:33]
	v_mfma_f32_16x16x32_bf16 v[10:13], v[238:241], v[148:151], v[10:13]
	v_mfma_f32_16x16x32_bf16 v[14:17], v[238:241], v[152:155], v[14:17]
	s_waitcnt vmcnt(0)
	s_barrier
; #define MFMA32(a, b, c) __builtin_amdgcn_mfma_f32_32x32x16_bf16((a), (b), (c), 0, 0, 0)
; DI void gemm256(const char* a_u, unsigned a_voff, size_t astep, const char* b_u, unsigned b_voff, size_t bstep, int nk, char* smem, f32x16 (&acc)[4][2]) {
;     ...
;   for (int kt = 0; kt < nk; ++kt) {
;     const int cur = kt & 1, k2 = (kt + 2 < last) ? kt + 2 : last;
;     const char* S = smem + cur * 2 * T2;
;     char* D = smem + (cur ^ 1) * 2 * T2;
;     const char* an = a_u + (size_t)k2 * 128;
;     const char* bn = b_u + (size_t)k2 * 128;
; #pragma unroll
;     for (int s = 0; s < 4; ++s) {
;       bf16x8 a[4], b[2];
; #pragma unroll
;       for (int mi = 0; mi < 4; ++mi) a[mi] = *(const bf16x8*)(S + aoff + mi * 32 * LROW + s * 32);
; #pragma unroll
;       for (int ni = 0; ni < 2; ++ni) b[ni] = *(const bf16x8*)(S + boff + ni * 32 * LROW + s * 32);
;       *(u32x4*)(D + soff + s * 64 * LROW) = ra[s];
;       *(u32x4*)(D + T2 + soff + s * 64 * LROW) = rb[s];
;       ra[s] = *(const u32x4*)(an + s * astep + a_voff);
;       rb[s] = *(const u32x4*)(bn + s * bstep + b_voff);
; #pragma unroll
;       for (int mi = 0; mi < 4; ++mi)
; #pragma unroll
;         for (int ni = 0; ni < 2; ++ni) acc[mi][ni] = MFMA32(a[mi], b[ni], acc[mi][ni]);
;     }
;     __syncthreads();
;   }
	ds_read_b128 v[196:199], v194 offset:32768
	ds_read_b128 v[212:215], v160 offset:32768
	ds_read_b128 v[216:219], v160 offset:34816
	ds_read_b128 v[242:245], v160 offset:36864
	ds_read_b128 v[246:249], v160 offset:38912
	ds_read_b128 v[200:203], v194 offset:36864
	ds_read_b128 v[204:207], v194 offset:40960
	ds_read_b128 v[208:211], v194 offset:45056
	s_add_i32 s56, s56, 1
	s_add_u32 m0, s59, 0x0
	s_nop 0
	global_load_lds_dwordx4 v164, s[54:55]
	s_add_u32 m0, s59, 0x400
	s_nop 0
	global_load_lds_dwordx4 v165, s[54:55]
	s_add_u32 m0, s59, 0x800
	s_nop 0
	global_load_lds_dwordx4 v130, s[54:55]
	s_add_u32 m0, s59, 0xc00
	s_nop 0
	global_load_lds_dwordx4 v131, s[54:55]
	s_waitcnt lgkmcnt(0)
	v_mfma_f32_16x16x32_bf16 v[114:117], v[196:199], v[212:215], v[114:117]
	ds_read_b128 v[220:223], v194 offset:34816
	v_mfma_f32_16x16x32_bf16 v[118:121], v[196:199], v[216:219], v[118:121]
	ds_read_b128 v[224:227], v194 offset:38912
	v_mfma_f32_16x16x32_bf16 v[98:101], v[196:199], v[242:245], v[98:101]
	ds_read_b128 v[228:231], v194 offset:43008
	v_mfma_f32_16x16x32_bf16 v[102:105], v[196:199], v[246:249], v[102:105]
	ds_read_b128 v[238:241], v194 offset:47104
	v_mfma_f32_16x16x32_bf16 v[82:85], v[200:203], v[212:215], v[82:85]
	v_mfma_f32_16x16x32_bf16 v[86:89], v[200:203], v[216:219], v[86:89]
	v_mfma_f32_16x16x32_bf16 v[66:69], v[200:203], v[242:245], v[66:69]
	v_mfma_f32_16x16x32_bf16 v[70:73], v[200:203], v[246:249], v[70:73]
	v_mfma_f32_16x16x32_bf16 v[50:53], v[204:207], v[212:215], v[50:53]
	v_mfma_f32_16x16x32_bf16 v[54:57], v[204:207], v[216:219], v[54:57]
	v_mfma_f32_16x16x32_bf16 v[34:37], v[204:207], v[242:245], v[34:37]
	v_mfma_f32_16x16x32_bf16 v[38:41], v[204:207], v[246:249], v[38:41]
	v_mfma_f32_16x16x32_bf16 v[18:21], v[208:211], v[212:215], v[18:21]
	v_mfma_f32_16x16x32_bf16 v[22:25], v[208:211], v[216:219], v[22:25]
	v_mfma_f32_16x16x32_bf16 v[2:5], v[208:211], v[242:245], v[2:5]
	v_mfma_f32_16x16x32_bf16 v[6:9], v[208:211], v[246:249], v[6:9]
	s_add_u32 m0, s58, 0x0
	s_nop 0
	global_load_lds_dwordx4 v164, s[52:53]
	s_add_u32 m0, s58, 0x400
	s_nop 0
	global_load_lds_dwordx4 v165, s[52:53]
	s_add_u32 m0, s58, 0x800
	s_nop 0
	global_load_lds_dwordx4 v130, s[52:53]
	s_add_u32 m0, s58, 0xc00
	s_nop 0
	global_load_lds_dwordx4 v131, s[52:53]
	s_waitcnt lgkmcnt(0)
	v_mfma_f32_16x16x32_bf16 v[122:125], v[220:223], v[212:215], v[122:125]
	ds_read_b128 v[196:199], v195 offset:32768
	v_mfma_f32_16x16x32_bf16 v[126:129], v[220:223], v[216:219], v[126:129]
	ds_read_b128 v[140:143], v161 offset:32768
	v_mfma_f32_16x16x32_bf16 v[106:109], v[220:223], v[242:245], v[106:109]
	ds_read_b128 v[144:147], v161 offset:34816
	v_mfma_f32_16x16x32_bf16 v[110:113], v[220:223], v[246:249], v[110:113]
	ds_read_b128 v[148:151], v161 offset:36864
	v_mfma_f32_16x16x32_bf16 v[90:93], v[224:227], v[212:215], v[90:93]
	ds_read_b128 v[152:155], v161 offset:38912
	v_mfma_f32_16x16x32_bf16 v[94:97], v[224:227], v[216:219], v[94:97]
	ds_read_b128 v[200:203], v195 offset:36864
	v_mfma_f32_16x16x32_bf16 v[74:77], v[224:227], v[242:245], v[74:77]
	ds_read_b128 v[204:207], v195 offset:40960
	v_mfma_f32_16x16x32_bf16 v[78:81], v[224:227], v[246:249], v[78:81]
	ds_read_b128 v[208:211], v195 offset:45056
	v_mfma_f32_16x16x32_bf16 v[58:61], v[228:231], v[212:215], v[58:61]
	v_mfma_f32_16x16x32_bf16 v[62:65], v[228:231], v[216:219], v[62:65]
	v_mfma_f32_16x16x32_bf16 v[42:45], v[228:231], v[242:245], v[42:45]
	v_mfma_f32_16x16x32_bf16 v[46:49], v[228:231], v[246:249], v[46:49]
	v_mfma_f32_16x16x32_bf16 v[26:29], v[238:241], v[212:215], v[26:29]
	v_mfma_f32_16x16x32_bf16 v[30:33], v[238:241], v[216:219], v[30:33]
	v_mfma_f32_16x16x32_bf16 v[10:13], v[238:241], v[242:245], v[10:13]
	v_mfma_f32_16x16x32_bf16 v[14:17], v[238:241], v[246:249], v[14:17]
	s_waitcnt lgkmcnt(0)
	v_mfma_f32_16x16x32_bf16 v[114:117], v[196:199], v[140:143], v[114:117]
	ds_read_b128 v[220:223], v195 offset:34816
	v_mfma_f32_16x16x32_bf16 v[118:121], v[196:199], v[144:147], v[118:121]
	ds_read_b128 v[224:227], v195 offset:38912
	v_mfma_f32_16x16x32_bf16 v[98:101], v[196:199], v[148:151], v[98:101]
	ds_read_b128 v[228:231], v195 offset:43008
	v_mfma_f32_16x16x32_bf16 v[102:105], v[196:199], v[152:155], v[102:105]
	ds_read_b128 v[238:241], v195 offset:47104
	v_mfma_f32_16x16x32_bf16 v[82:85], v[200:203], v[140:143], v[82:85]
	v_mfma_f32_16x16x32_bf16 v[86:89], v[200:203], v[144:147], v[86:89]
	v_mfma_f32_16x16x32_bf16 v[66:69], v[200:203], v[148:151], v[66:69]
	v_mfma_f32_16x16x32_bf16 v[70:73], v[200:203], v[152:155], v[70:73]
	v_mfma_f32_16x16x32_bf16 v[50:53], v[204:207], v[140:143], v[50:53]
	v_mfma_f32_16x16x32_bf16 v[54:57], v[204:207], v[144:147], v[54:57]
	s_cmp_lt_u32 s56, s57
	s_cselect_b32 s60, 0x80, 0
	s_add_u32 s52, s52, s60
	s_addc_u32 s53, s53, 0
	s_add_u32 s54, s54, s60
	s_addc_u32 s55, s55, 0
	v_mfma_f32_16x16x32_bf16 v[34:37], v[204:207], v[148:151], v[34:37]
	v_mfma_f32_16x16x32_bf16 v[38:41], v[204:207], v[152:155], v[38:41]
	v_mfma_f32_16x16x32_bf16 v[18:21], v[208:211], v[140:143], v[18:21]
	v_mfma_f32_16x16x32_bf16 v[22:25], v[208:211], v[144:147], v[22:25]
	v_mfma_f32_16x16x32_bf16 v[2:5], v[208:211], v[148:151], v[2:5]
	v_mfma_f32_16x16x32_bf16 v[6:9], v[208:211], v[152:155], v[6:9]
	s_waitcnt lgkmcnt(0)
	v_mfma_f32_16x16x32_bf16 v[122:125], v[220:223], v[140:143], v[122:125]
	v_mfma_f32_16x16x32_bf16 v[126:129], v[220:223], v[144:147], v[126:129]
	v_mfma_f32_16x16x32_bf16 v[106:109], v[220:223], v[148:151], v[106:109]
	v_mfma_f32_16x16x32_bf16 v[110:113], v[220:223], v[152:155], v[110:113]
	v_mfma_f32_16x16x32_bf16 v[90:93], v[224:227], v[140:143], v[90:93]
	v_mfma_f32_16x16x32_bf16 v[94:97], v[224:227], v[144:147], v[94:97]
	v_mfma_f32_16x16x32_bf16 v[74:77], v[224:227], v[148:151], v[74:77]
	v_mfma_f32_16x16x32_bf16 v[78:81], v[224:227], v[152:155], v[78:81]
	v_mfma_f32_16x16x32_bf16 v[58:61], v[228:231], v[140:143], v[58:61]
	v_mfma_f32_16x16x32_bf16 v[62:65], v[228:231], v[144:147], v[62:65]
	v_mfma_f32_16x16x32_bf16 v[42:45], v[228:231], v[148:151], v[42:45]
	v_mfma_f32_16x16x32_bf16 v[46:49], v[228:231], v[152:155], v[46:49]
	v_mfma_f32_16x16x32_bf16 v[26:29], v[238:241], v[140:143], v[26:29]
	v_mfma_f32_16x16x32_bf16 v[30:33], v[238:241], v[144:147], v[30:33]
	v_mfma_f32_16x16x32_bf16 v[10:13], v[238:241], v[148:151], v[10:13]
	v_mfma_f32_16x16x32_bf16 v[14:17], v[238:241], v[152:155], v[14:17]
	s_waitcnt vmcnt(0)
	s_barrier
; #define MFMA32(a, b, c) __builtin_amdgcn_mfma_f32_32x32x16_bf16((a), (b), (c), 0, 0, 0)
; DI void gemm256(const char* a_u, unsigned a_voff, size_t astep, const char* b_u, unsigned b_voff, size_t bstep, int nk, char* smem, f32x16 (&acc)[4][2]) {
;     ...
;   for (int kt = 0; kt < nk; ++kt) {
;     const int cur = kt & 1, k2 = (kt + 2 < last) ? kt + 2 : last;
;     const char* S = smem + cur * 2 * T2;
;     char* D = smem + (cur ^ 1) * 2 * T2;
;     const char* an = a_u + (size_t)k2 * 128;
;     const char* bn = b_u + (size_t)k2 * 128;
; #pragma unroll
;     for (int s = 0; s < 4; ++s) {
;       bf16x8 a[4], b[2];
; #pragma unroll
;       for (int mi = 0; mi < 4; ++mi) a[mi] = *(const bf16x8*)(S + aoff + mi * 32 * LROW + s * 32);
; #pragma unroll
;       for (int ni = 0; ni < 2; ++ni) b[ni] = *(const bf16x8*)(S + boff + ni * 32 * LROW + s * 32);
;       *(u32x4*)(D + soff + s * 64 * LROW) = ra[s];
;       *(u32x4*)(D + T2 + soff + s * 64 * LROW) = rb[s];
;       ra[s] = *(const u32x4*)(an + s * astep + a_voff);
;       rb[s] = *(const u32x4*)(bn + s * bstep + b_voff);
; #pragma unroll
;       for (int mi = 0; mi < 4; ++mi)
; #pragma unroll
;         for (int ni = 0; ni < 2; ++ni) acc[mi][ni] = MFMA32(a[mi], b[ni], acc[mi][ni]);
;     }
;     __syncthreads();
;   }
	ds_read_b128 v[196:199], v194 offset:0
	ds_read_b128 v[212:215], v160 offset:0
	ds_read_b128 v[216:219], v160 offset:2048
	ds_read_b128 v[242:245], v160 offset:4096
	ds_read_b128 v[246:249], v160 offset:6144
	ds_read_b128 v[200:203], v194 offset:4096
	ds_read_b128 v[204:207], v194 offset:8192
	ds_read_b128 v[208:211], v194 offset:12288
	s_cmp_lt_u32 s56, s57
	s_cbranch_scc1 .Lg_outproj_loop
	s_waitcnt vmcnt(0) lgkmcnt(0)
	s_nop 7
	s_nop 7
	v_permlane16_swap_b32_e32 v114, v118
	v_permlane16_swap_b32_e32 v115, v119
	v_permlane16_swap_b32_e32 v116, v120
	v_permlane16_swap_b32_e32 v117, v121
	v_permlane16_swap_b32_e32 v122, v126
	v_permlane16_swap_b32_e32 v123, v127
	v_permlane16_swap_b32_e32 v124, v128
	v_permlane16_swap_b32_e32 v125, v129
	v_permlane16_swap_b32_e32 v98, v102
	v_permlane16_swap_b32_e32 v99, v103
	v_permlane16_swap_b32_e32 v100, v104
	v_permlane16_swap_b32_e32 v101, v105
	v_permlane16_swap_b32_e32 v106, v110
	v_permlane16_swap_b32_e32 v107, v111
	v_permlane16_swap_b32_e32 v108, v112
	v_permlane16_swap_b32_e32 v109, v113
	v_permlane16_swap_b32_e32 v82, v86
	v_permlane16_swap_b32_e32 v83, v87
	v_permlane16_swap_b32_e32 v84, v88
	v_permlane16_swap_b32_e32 v85, v89
	v_permlane16_swap_b32_e32 v90, v94
	v_permlane16_swap_b32_e32 v91, v95
	v_permlane16_swap_b32_e32 v92, v96
	v_permlane16_swap_b32_e32 v93, v97
	v_permlane16_swap_b32_e32 v66, v70
	v_permlane16_swap_b32_e32 v67, v71
	v_permlane16_swap_b32_e32 v68, v72
	v_permlane16_swap_b32_e32 v69, v73
	v_permlane16_swap_b32_e32 v74, v78
	v_permlane16_swap_b32_e32 v75, v79
	v_permlane16_swap_b32_e32 v76, v80
	v_permlane16_swap_b32_e32 v77, v81
	v_permlane16_swap_b32_e32 v50, v54
	v_permlane16_swap_b32_e32 v51, v55
	v_permlane16_swap_b32_e32 v52, v56
	v_permlane16_swap_b32_e32 v53, v57
	v_permlane16_swap_b32_e32 v58, v62
	v_permlane16_swap_b32_e32 v59, v63
	v_permlane16_swap_b32_e32 v60, v64
	v_permlane16_swap_b32_e32 v61, v65
	v_permlane16_swap_b32_e32 v34, v38
	v_permlane16_swap_b32_e32 v35, v39
	v_permlane16_swap_b32_e32 v36, v40
	v_permlane16_swap_b32_e32 v37, v41
	v_permlane16_swap_b32_e32 v42, v46
	v_permlane16_swap_b32_e32 v43, v47
	v_permlane16_swap_b32_e32 v44, v48
	v_permlane16_swap_b32_e32 v45, v49
	v_permlane16_swap_b32_e32 v18, v22
	v_permlane16_swap_b32_e32 v19, v23
	v_permlane16_swap_b32_e32 v20, v24
	v_permlane16_swap_b32_e32 v21, v25
	v_permlane16_swap_b32_e32 v26, v30
	v_permlane16_swap_b32_e32 v27, v31
	v_permlane16_swap_b32_e32 v28, v32
	v_permlane16_swap_b32_e32 v29, v33
	v_permlane16_swap_b32_e32 v2, v6
	v_permlane16_swap_b32_e32 v3, v7
	v_permlane16_swap_b32_e32 v4, v8
	v_permlane16_swap_b32_e32 v5, v9
	v_permlane16_swap_b32_e32 v10, v14
	v_permlane16_swap_b32_e32 v11, v15
	v_permlane16_swap_b32_e32 v12, v16
	v_permlane16_swap_b32_e32 v13, v17
	v_permlane32_swap_b32_e32 v114, v118
	v_permlane32_swap_b32_e32 v115, v119
	v_permlane32_swap_b32_e32 v116, v120
	v_permlane32_swap_b32_e32 v117, v121
	v_permlane32_swap_b32_e32 v122, v126
	v_permlane32_swap_b32_e32 v123, v127
	v_permlane32_swap_b32_e32 v124, v128
	v_permlane32_swap_b32_e32 v125, v129
	v_permlane32_swap_b32_e32 v98, v102
	v_permlane32_swap_b32_e32 v99, v103
	v_permlane32_swap_b32_e32 v100, v104
	v_permlane32_swap_b32_e32 v101, v105
	v_permlane32_swap_b32_e32 v106, v110
	v_permlane32_swap_b32_e32 v107, v111
	v_permlane32_swap_b32_e32 v108, v112
	v_permlane32_swap_b32_e32 v109, v113
	v_permlane32_swap_b32_e32 v82, v86
	v_permlane32_swap_b32_e32 v83, v87
	v_permlane32_swap_b32_e32 v84, v88
	v_permlane32_swap_b32_e32 v85, v89
	v_permlane32_swap_b32_e32 v90, v94
	v_permlane32_swap_b32_e32 v91, v95
	v_permlane32_swap_b32_e32 v92, v96
	v_permlane32_swap_b32_e32 v93, v97
	v_permlane32_swap_b32_e32 v66, v70
	v_permlane32_swap_b32_e32 v67, v71
	v_permlane32_swap_b32_e32 v68, v72
	v_permlane32_swap_b32_e32 v69, v73
	v_permlane32_swap_b32_e32 v74, v78
	v_permlane32_swap_b32_e32 v75, v79
	v_permlane32_swap_b32_e32 v76, v80
	v_permlane32_swap_b32_e32 v77, v81
	v_permlane32_swap_b32_e32 v50, v54
	v_permlane32_swap_b32_e32 v51, v55
	v_permlane32_swap_b32_e32 v52, v56
	v_permlane32_swap_b32_e32 v53, v57
	v_permlane32_swap_b32_e32 v58, v62
	v_permlane32_swap_b32_e32 v59, v63
	v_permlane32_swap_b32_e32 v60, v64
	v_permlane32_swap_b32_e32 v61, v65
	v_permlane32_swap_b32_e32 v34, v38
	v_permlane32_swap_b32_e32 v35, v39
	v_permlane32_swap_b32_e32 v36, v40
	v_permlane32_swap_b32_e32 v37, v41
	v_permlane32_swap_b32_e32 v42, v46
	v_permlane32_swap_b32_e32 v43, v47
	v_permlane32_swap_b32_e32 v44, v48
	v_permlane32_swap_b32_e32 v45, v49
	v_permlane32_swap_b32_e32 v18, v22
	v_permlane32_swap_b32_e32 v19, v23
	v_permlane32_swap_b32_e32 v20, v24
	v_permlane32_swap_b32_e32 v21, v25
	v_permlane32_swap_b32_e32 v26, v30
	v_permlane32_swap_b32_e32 v27, v31
	v_permlane32_swap_b32_e32 v28, v32
	v_permlane32_swap_b32_e32 v29, v33
	v_permlane32_swap_b32_e32 v2, v6
	v_permlane32_swap_b32_e32 v3, v7
	v_permlane32_swap_b32_e32 v4, v8
	v_permlane32_swap_b32_e32 v5, v9
	v_permlane32_swap_b32_e32 v10, v14
	v_permlane32_swap_b32_e32 v11, v15
	v_permlane32_swap_b32_e32 v12, v16
	v_permlane32_swap_b32_e32 v13, v17
	s_nop 1
	s_branch .LBB0_925

; #define MFMA32(a, b, c) __builtin_amdgcn_mfma_f32_32x32x16_bf16((a), (b), (c), 0, 0, 0)
; DI void gemm256(const char* a_u, unsigned a_voff, size_t astep, const char* b_u, unsigned b_voff, size_t bstep, int nk, char* smem, f32x16 (&acc)[4][2]) {
;     ...
;   for (int kt = 0; kt < nk; ++kt) {
;     const int cur = kt & 1, k2 = (kt + 2 < last) ? kt + 2 : last;
;     const char* S = smem + cur * 2 * T2;
;     char* D = smem + (cur ^ 1) * 2 * T2;
;     const char* an = a_u + (size_t)k2 * 128;
;     const char* bn = b_u + (size_t)k2 * 128;
; #pragma unroll
;     for (int s = 0; s < 4; ++s) {
;       bf16x8 a[4], b[2];
; #pragma unroll
;       for (int mi = 0; mi < 4; ++mi) a[mi] = *(const bf16x8*)(S + aoff + mi * 32 * LROW + s * 32);
; #pragma unroll
;       for (int ni = 0; ni < 2; ++ni) b[ni] = *(const bf16x8*)(S + boff + ni * 32 * LROW + s * 32);
;       *(u32x4*)(D + soff + s * 64 * LROW) = ra[s];
;       *(u32x4*)(D + T2 + soff + s * 64 * LROW) = rb[s];
;       ra[s] = *(const u32x4*)(an + s * astep + a_voff);
;       rb[s] = *(const u32x4*)(bn + s * bstep + b_voff);
; #pragma unroll
;       for (int mi = 0; mi < 4; ++mi)
; #pragma unroll
;         for (int ni = 0; ni < 2; ++ni) acc[mi][ni] = MFMA32(a[mi], b[ni], acc[mi][ni]);
;     }
;     __syncthreads();
;   }
.Lg_gateup_loop:
	s_add_i32 s56, s56, 1
	s_add_u32 m0, s59, 0x8000
	s_nop 0
	global_load_lds_dwordx4 v164, s[54:55]
	s_add_u32 m0, s59, 0x8400
	s_nop 0
	global_load_lds_dwordx4 v165, s[54:55]
	s_add_u32 m0, s59, 0x8800
	s_nop 0
	global_load_lds_dwordx4 v130, s[54:55]
	s_add_u32 m0, s59, 0x8c00
	s_nop 0
	global_load_lds_dwordx4 v131, s[54:55]
	s_waitcnt lgkmcnt(0)
	v_mfma_f32_16x16x32_bf16 v[114:117], v[196:199], v[212:215], v[114:117]
	ds_read_b128 v[220:223], v194 offset:2048
	v_mfma_f32_16x16x32_bf16 v[118:121], v[196:199], v[216:219], v[118:121]
	ds_read_b128 v[224:227], v194 offset:6144
	v_mfma_f32_16x16x32_bf16 v[98:101], v[196:199], v[242:245], v[98:101]
	ds_read_b128 v[228:231], v194 offset:10240
	v_mfma_f32_16x16x32_bf16 v[102:105], v[196:199], v[246:249], v[102:105]
	ds_read_b128 v[238:241], v194 offset:14336
	v_mfma_f32_16x16x32_bf16 v[82:85], v[200:203], v[212:215], v[82:85]
	v_mfma_f32_16x16x32_bf16 v[86:89], v[200:203], v[216:219], v[86:89]
	v_mfma_f32_16x16x32_bf16 v[66:69], v[200:203], v[242:245], v[66:69]
	v_mfma_f32_16x16x32_bf16 v[70:73], v[200:203], v[246:249], v[70:73]
	v_mfma_f32_16x16x32_bf16 v[50:53], v[204:207], v[212:215], v[50:53]
	v_mfma_f32_16x16x32_bf16 v[54:57], v[204:207], v[216:219], v[54:57]
	v_mfma_f32_16x16x32_bf16 v[34:37], v[204:207], v[242:245], v[34:37]
	v_mfma_f32_16x16x32_bf16 v[38:41], v[204:207], v[246:249], v[38:41]
	v_mfma_f32_16x16x32_bf16 v[18:21], v[208:211], v[212:215], v[18:21]
	v_mfma_f32_16x16x32_bf16 v[22:25], v[208:211], v[216:219], v[22:25]
	v_mfma_f32_16x16x32_bf16 v[2:5], v[208:211], v[242:245], v[2:5]
	v_mfma_f32_16x16x32_bf16 v[6:9], v[208:211], v[246:249], v[6:9]
	s_add_u32 m0, s58, 0x8000
	s_nop 0
	global_load_lds_dwordx4 v164, s[52:53]
	s_add_u32 m0, s58, 0x8400
	s_nop 0
	global_load_lds_dwordx4 v165, s[52:53]
	s_add_u32 m0, s58, 0x8800
	s_nop 0
	global_load_lds_dwordx4 v130, s[52:53]
	s_add_u32 m0, s58, 0x8c00
	s_nop 0
	global_load_lds_dwordx4 v131, s[52:53]
	s_waitcnt lgkmcnt(0)
	v_mfma_f32_16x16x32_bf16 v[122:125], v[220:223], v[212:215], v[122:125]
	ds_read_b128 v[196:199], v195 offset:0
	v_mfma_f32_16x16x32_bf16 v[126:129], v[220:223], v[216:219], v[126:129]
	ds_read_b128 v[140:143], v161 offset:0
	v_mfma_f32_16x16x32_bf16 v[106:109], v[220:223], v[242:245], v[106:109]
	ds_read_b128 v[144:147], v161 offset:2048
	v_mfma_f32_16x16x32_bf16 v[110:113], v[220:223], v[246:249], v[110:113]
	ds_read_b128 v[148:151], v161 offset:4096
	v_mfma_f32_16x16x32_bf16 v[90:93], v[224:227], v[212:215], v[90:93]
	ds_read_b128 v[152:155], v161 offset:6144
	v_mfma_f32_16x16x32_bf16 v[94:97], v[224:227], v[216:219], v[94:97]
	ds_read_b128 v[200:203], v195 offset:4096
	v_mfma_f32_16x16x32_bf16 v[74:77], v[224:227], v[242:245], v[74:77]
	ds_read_b128 v[204:207], v195 offset:8192
	v_mfma_f32_16x16x32_bf16 v[78:81], v[224:227], v[246:249], v[78:81]
	ds_read_b128 v[208:211], v195 offset:12288
	v_mfma_f32_16x16x32_bf16 v[58:61], v[228:231], v[212:215], v[58:61]
	v_mfma_f32_16x16x32_bf16 v[62:65], v[228:231], v[216:219], v[62:65]
	v_mfma_f32_16x16x32_bf16 v[42:45], v[228:231], v[242:245], v[42:45]
	v_mfma_f32_16x16x32_bf16 v[46:49], v[228:231], v[246:249], v[46:49]
	v_mfma_f32_16x16x32_bf16 v[26:29], v[238:241], v[212:215], v[26:29]
	v_mfma_f32_16x16x32_bf16 v[30:33], v[238:241], v[216:219], v[30:33]
	v_mfma_f32_16x16x32_bf16 v[10:13], v[238:241], v[242:245], v[10:13]
	v_mfma_f32_16x16x32_bf16 v[14:17], v[238:241], v[246:249], v[14:17]
	s_waitcnt lgkmcnt(0)
	v_mfma_f32_16x16x32_bf16 v[114:117], v[196:199], v[140:143], v[114:117]
	ds_read_b128 v[220:223], v195 offset:2048
	v_mfma_f32_16x16x32_bf16 v[118:121], v[196:199], v[144:147], v[118:121]
	ds_read_b128 v[224:227], v195 offset:6144
	v_mfma_f32_16x16x32_bf16 v[98:101], v[196:199], v[148:151], v[98:101]
	ds_read_b128 v[228:231], v195 offset:10240
	v_mfma_f32_16x16x32_bf16 v[102:105], v[196:199], v[152:155], v[102:105]
	ds_read_b128 v[238:241], v195 offset:14336
	v_mfma_f32_16x16x32_bf16 v[82:85], v[200:203], v[140:143], v[82:85]
	v_mfma_f32_16x16x32_bf16 v[86:89], v[200:203], v[144:147], v[86:89]
	v_mfma_f32_16x16x32_bf16 v[66:69], v[200:203], v[148:151], v[66:69]
	v_mfma_f32_16x16x32_bf16 v[70:73], v[200:203], v[152:155], v[70:73]
	v_mfma_f32_16x16x32_bf16 v[50:53], v[204:207], v[140:143], v[50:53]
	v_mfma_f32_16x16x32_bf16 v[54:57], v[204:207], v[144:147], v[54:57]
	s_cmp_lt_u32 s56, s57
	s_cselect_b32 s60, 0x80, 0
	s_add_u32 s52, s52, s60
	s_addc_u32 s53, s53, 0
	s_add_u32 s54, s54, s60
	s_addc_u32 s55, s55, 0
	s_cmp_eq_u32 s56, s63
	s_cselect_b32 s52, s64, s52
	s_cselect_b32 s53, s65, s53
	s_cselect_b32 s54, s66, s54
	s_cselect_b32 s55, s67, s55
	v_mfma_f32_16x16x32_bf16 v[34:37], v[204:207], v[148:151], v[34:37]
	v_mfma_f32_16x16x32_bf16 v[38:41], v[204:207], v[152:155], v[38:41]
	v_mfma_f32_16x16x32_bf16 v[18:21], v[208:211], v[140:143], v[18:21]
	v_mfma_f32_16x16x32_bf16 v[22:25], v[208:211], v[144:147], v[22:25]
	v_mfma_f32_16x16x32_bf16 v[2:5], v[208:211], v[148:151], v[2:5]
	v_mfma_f32_16x16x32_bf16 v[6:9], v[208:211], v[152:155], v[6:9]
	s_waitcnt lgkmcnt(0)
	v_mfma_f32_16x16x32_bf16 v[122:125], v[220:223], v[140:143], v[122:125]
	v_mfma_f32_16x16x32_bf16 v[126:129], v[220:223], v[144:147], v[126:129]
	v_mfma_f32_16x16x32_bf16 v[106:109], v[220:223], v[148:151], v[106:109]
	v_mfma_f32_16x16x32_bf16 v[110:113], v[220:223], v[152:155], v[110:113]
	v_mfma_f32_16x16x32_bf16 v[90:93], v[224:227], v[140:143], v[90:93]
	v_mfma_f32_16x16x32_bf16 v[94:97], v[224:227], v[144:147], v[94:97]
	v_mfma_f32_16x16x32_bf16 v[74:77], v[224:227], v[148:151], v[74:77]
	v_mfma_f32_16x16x32_bf16 v[78:81], v[224:227], v[152:155], v[78:81]
	v_mfma_f32_16x16x32_bf16 v[58:61], v[228:231], v[140:143], v[58:61]
	v_mfma_f32_16x16x32_bf16 v[62:65], v[228:231], v[144:147], v[62:65]
	v_mfma_f32_16x16x32_bf16 v[42:45], v[228:231], v[148:151], v[42:45]
	v_mfma_f32_16x16x32_bf16 v[46:49], v[228:231], v[152:155], v[46:49]
	v_mfma_f32_16x16x32_bf16 v[26:29], v[238:241], v[140:143], v[26:29]
	v_mfma_f32_16x16x32_bf16 v[30:33], v[238:241], v[144:147], v[30:33]
	v_mfma_f32_16x16x32_bf16 v[10:13], v[238:241], v[148:151], v[10:13]
	v_mfma_f32_16x16x32_bf16 v[14:17], v[238:241], v[152:155], v[14:17]
	s_waitcnt vmcnt(0)
	s_barrier
; #define MFMA32(a, b, c) __builtin_amdgcn_mfma_f32_32x32x16_bf16((a), (b), (c), 0, 0, 0)
; DI void gemm256(const char* a_u, unsigned a_voff, size_t astep, const char* b_u, unsigned b_voff, size_t bstep, int nk, char* smem, f32x16 (&acc)[4][2]) {
;     ...
;   for (int kt = 0; kt < nk; ++kt) {
;     const int cur = kt & 1, k2 = (kt + 2 < last) ? kt + 2 : last;
;     const char* S = smem + cur * 2 * T2;
;     char* D = smem + (cur ^ 1) * 2 * T2;
;     const char* an = a_u + (size_t)k2 * 128;
;     const char* bn = b_u + (size_t)k2 * 128;
; #pragma unroll
;     for (int s = 0; s < 4; ++s) {
;       bf16x8 a[4], b[2];
; #pragma unroll
;       for (int mi = 0; mi < 4; ++mi) a[mi] = *(const bf16x8*)(S + aoff + mi * 32 * LROW + s * 32);
; #pragma unroll
;       for (int ni = 0; ni < 2; ++ni) b[ni] = *(const bf16x8*)(S + boff + ni * 32 * LROW + s * 32);
;       *(u32x4*)(D + soff + s * 64 * LROW) = ra[s];
;       *(u32x4*)(D + T2 + soff + s * 64 * LROW) = rb[s];
;       ra[s] = *(const u32x4*)(an + s * astep + a_voff);
;       rb[s] = *(const u32x4*)(bn + s * bstep + b_voff);
; #pragma unroll
;       for (int mi = 0; mi < 4; ++mi)
; #pragma unroll
;         for (int ni = 0; ni < 2; ++ni) acc[mi][ni] = MFMA32(a[mi], b[ni], acc[mi][ni]);
;     }
;     __syncthreads();
;   }
	ds_read_b128 v[196:199], v194 offset:32768
	ds_read_b128 v[212:215], v160 offset:32768
	ds_read_b128 v[216:219], v160 offset:34816
	ds_read_b128 v[242:245], v160 offset:36864
	ds_read_b128 v[246:249], v160 offset:38912
	ds_read_b128 v[200:203], v194 offset:36864
	ds_read_b128 v[204:207], v194 offset:40960
	ds_read_b128 v[208:211], v194 offset:45056
	s_add_i32 s56, s56, 1
	s_add_u32 m0, s59, 0x0
	s_nop 0
	global_load_lds_dwordx4 v164, s[54:55]
	s_add_u32 m0, s59, 0x400
	s_nop 0
	global_load_lds_dwordx4 v165, s[54:55]
	s_add_u32 m0, s59, 0x800
	s_nop 0
	global_load_lds_dwordx4 v130, s[54:55]
	s_add_u32 m0, s59, 0xc00
	s_nop 0
	global_load_lds_dwordx4 v131, s[54:55]
	s_waitcnt lgkmcnt(0)
	v_mfma_f32_16x16x32_bf16 v[114:117], v[196:199], v[212:215], v[114:117]
	ds_read_b128 v[220:223], v194 offset:34816
	v_mfma_f32_16x16x32_bf16 v[118:121], v[196:199], v[216:219], v[118:121]
	ds_read_b128 v[224:227], v194 offset:38912
	v_mfma_f32_16x16x32_bf16 v[98:101], v[196:199], v[242:245], v[98:101]
	ds_read_b128 v[228:231], v194 offset:43008
	v_mfma_f32_16x16x32_bf16 v[102:105], v[196:199], v[246:249], v[102:105]
	ds_read_b128 v[238:241], v194 offset:47104
	v_mfma_f32_16x16x32_bf16 v[82:85], v[200:203], v[212:215], v[82:85]
	v_mfma_f32_16x16x32_bf16 v[86:89], v[200:203], v[216:219], v[86:89]
	v_mfma_f32_16x16x32_bf16 v[66:69], v[200:203], v[242:245], v[66:69]
	v_mfma_f32_16x16x32_bf16 v[70:73], v[200:203], v[246:249], v[70:73]
	v_mfma_f32_16x16x32_bf16 v[50:53], v[204:207], v[212:215], v[50:53]
	v_mfma_f32_16x16x32_bf16 v[54:57], v[204:207], v[216:219], v[54:57]
	v_mfma_f32_16x16x32_bf16 v[34:37], v[204:207], v[242:245], v[34:37]
	v_mfma_f32_16x16x32_bf16 v[38:41], v[204:207], v[246:249], v[38:41]
	v_mfma_f32_16x16x32_bf16 v[18:21], v[208:211], v[212:215], v[18:21]
	v_mfma_f32_16x16x32_bf16 v[22:25], v[208:211], v[216:219], v[22:25]
	v_mfma_f32_16x16x32_bf16 v[2:5], v[208:211], v[242:245], v[2:5]
	v_mfma_f32_16x16x32_bf16 v[6:9], v[208:211], v[246:249], v[6:9]
	s_add_u32 m0, s58, 0x0
	s_nop 0
	global_load_lds_dwordx4 v164, s[52:53]
	s_add_u32 m0, s58, 0x400
	s_nop 0
	global_load_lds_dwordx4 v165, s[52:53]
	s_add_u32 m0, s58, 0x800
	s_nop 0
	global_load_lds_dwordx4 v130, s[52:53]
	s_add_u32 m0, s58, 0xc00
	s_nop 0
	global_load_lds_dwordx4 v131, s[52:53]
	s_waitcnt lgkmcnt(0)
	v_mfma_f32_16x16x32_bf16 v[122:125], v[220:223], v[212:215], v[122:125]
	ds_read_b128 v[196:199], v195 offset:32768
	v_mfma_f32_16x16x32_bf16 v[126:129], v[220:223], v[216:219], v[126:129]
	ds_read_b128 v[140:143], v161 offset:32768
	v_mfma_f32_16x16x32_bf16 v[106:109], v[220:223], v[242:245], v[106:109]
	ds_read_b128 v[144:147], v161 offset:34816
	v_mfma_f32_16x16x32_bf16 v[110:113], v[220:223], v[246:249], v[110:113]
	ds_read_b128 v[148:151], v161 offset:36864
	v_mfma_f32_16x16x32_bf16 v[90:93], v[224:227], v[212:215], v[90:93]
	ds_read_b128 v[152:155], v161 offset:38912
	v_mfma_f32_16x16x32_bf16 v[94:97], v[224:227], v[216:219], v[94:97]
	ds_read_b128 v[200:203], v195 offset:36864
	v_mfma_f32_16x16x32_bf16 v[74:77], v[224:227], v[242:245], v[74:77]
	ds_read_b128 v[204:207], v195 offset:40960
	v_mfma_f32_16x16x32_bf16 v[78:81], v[224:227], v[246:249], v[78:81]
	ds_read_b128 v[208:211], v195 offset:45056
	v_mfma_f32_16x16x32_bf16 v[58:61], v[228:231], v[212:215], v[58:61]
	v_mfma_f32_16x16x32_bf16 v[62:65], v[228:231], v[216:219], v[62:65]
	v_mfma_f32_16x16x32_bf16 v[42:45], v[228:231], v[242:245], v[42:45]
	v_mfma_f32_16x16x32_bf16 v[46:49], v[228:231], v[246:249], v[46:49]
	v_mfma_f32_16x16x32_bf16 v[26:29], v[238:241], v[212:215], v[26:29]
	v_mfma_f32_16x16x32_bf16 v[30:33], v[238:241], v[216:219], v[30:33]
	v_mfma_f32_16x16x32_bf16 v[10:13], v[238:241], v[242:245], v[10:13]
	v_mfma_f32_16x16x32_bf16 v[14:17], v[238:241], v[246:249], v[14:17]
	s_waitcnt lgkmcnt(0)
	v_mfma_f32_16x16x32_bf16 v[114:117], v[196:199], v[140:143], v[114:117]
	ds_read_b128 v[220:223], v195 offset:34816
	v_mfma_f32_16x16x32_bf16 v[118:121], v[196:199], v[144:147], v[118:121]
	ds_read_b128 v[224:227], v195 offset:38912
	v_mfma_f32_16x16x32_bf16 v[98:101], v[196:199], v[148:151], v[98:101]
	ds_read_b128 v[228:231], v195 offset:43008
	v_mfma_f32_16x16x32_bf16 v[102:105], v[196:199], v[152:155], v[102:105]
	ds_read_b128 v[238:241], v195 offset:47104
	v_mfma_f32_16x16x32_bf16 v[82:85], v[200:203], v[140:143], v[82:85]
	v_mfma_f32_16x16x32_bf16 v[86:89], v[200:203], v[144:147], v[86:89]
	v_mfma_f32_16x16x32_bf16 v[66:69], v[200:203], v[148:151], v[66:69]
	v_mfma_f32_16x16x32_bf16 v[70:73], v[200:203], v[152:155], v[70:73]
	v_mfma_f32_16x16x32_bf16 v[50:53], v[204:207], v[140:143], v[50:53]
	v_mfma_f32_16x16x32_bf16 v[54:57], v[204:207], v[144:147], v[54:57]
	s_cmp_lt_u32 s56, s57
	s_cselect_b32 s60, 0x80, 0
	s_add_u32 s52, s52, s60
	s_addc_u32 s53, s53, 0
	s_add_u32 s54, s54, s60
	s_addc_u32 s55, s55, 0
	s_cmp_eq_u32 s56, s63
	s_cselect_b32 s52, s64, s52
	s_cselect_b32 s53, s65, s53
	s_cselect_b32 s54, s66, s54
	s_cselect_b32 s55, s67, s55
	v_mfma_f32_16x16x32_bf16 v[34:37], v[204:207], v[148:151], v[34:37]
	v_mfma_f32_16x16x32_bf16 v[38:41], v[204:207], v[152:155], v[38:41]
	v_mfma_f32_16x16x32_bf16 v[18:21], v[208:211], v[140:143], v[18:21]
	v_mfma_f32_16x16x32_bf16 v[22:25], v[208:211], v[144:147], v[22:25]
	v_mfma_f32_16x16x32_bf16 v[2:5], v[208:211], v[148:151], v[2:5]
	v_mfma_f32_16x16x32_bf16 v[6:9], v[208:211], v[152:155], v[6:9]
	s_waitcnt lgkmcnt(0)
	v_mfma_f32_16x16x32_bf16 v[122:125], v[220:223], v[140:143], v[122:125]
	v_mfma_f32_16x16x32_bf16 v[126:129], v[220:223], v[144:147], v[126:129]
	v_mfma_f32_16x16x32_bf16 v[106:109], v[220:223], v[148:151], v[106:109]
	v_mfma_f32_16x16x32_bf16 v[110:113], v[220:223], v[152:155], v[110:113]
	v_mfma_f32_16x16x32_bf16 v[90:93], v[224:227], v[140:143], v[90:93]
	v_mfma_f32_16x16x32_bf16 v[94:97], v[224:227], v[144:147], v[94:97]
	v_mfma_f32_16x16x32_bf16 v[74:77], v[224:227], v[148:151], v[74:77]
	v_mfma_f32_16x16x32_bf16 v[78:81], v[224:227], v[152:155], v[78:81]
	v_mfma_f32_16x16x32_bf16 v[58:61], v[228:231], v[140:143], v[58:61]
	v_mfma_f32_16x16x32_bf16 v[62:65], v[228:231], v[144:147], v[62:65]
	v_mfma_f32_16x16x32_bf16 v[42:45], v[228:231], v[148:151], v[42:45]
	v_mfma_f32_16x16x32_bf16 v[46:49], v[228:231], v[152:155], v[46:49]
	v_mfma_f32_16x16x32_bf16 v[26:29], v[238:241], v[140:143], v[26:29]
	v_mfma_f32_16x16x32_bf16 v[30:33], v[238:241], v[144:147], v[30:33]
	v_mfma_f32_16x16x32_bf16 v[10:13], v[238:241], v[148:151], v[10:13]
	v_mfma_f32_16x16x32_bf16 v[14:17], v[238:241], v[152:155], v[14:17]
	s_waitcnt vmcnt(0)
	s_barrier
; #define MFMA32(a, b, c) __builtin_amdgcn_mfma_f32_32x32x16_bf16((a), (b), (c), 0, 0, 0)
; DI void gemm256(const char* a_u, unsigned a_voff, size_t astep, const char* b_u, unsigned b_voff, size_t bstep, int nk, char* smem, f32x16 (&acc)[4][2]) {
;     ...
;   for (int kt = 0; kt < nk; ++kt) {
;     const int cur = kt & 1, k2 = (kt + 2 < last) ? kt + 2 : last;
;     const char* S = smem + cur * 2 * T2;
;     char* D = smem + (cur ^ 1) * 2 * T2;
;     const char* an = a_u + (size_t)k2 * 128;
;     const char* bn = b_u + (size_t)k2 * 128;
; #pragma unroll
;     for (int s = 0; s < 4; ++s) {
;       bf16x8 a[4], b[2];
; #pragma unroll
;       for (int mi = 0; mi < 4; ++mi) a[mi] = *(const bf16x8*)(S + aoff + mi * 32 * LROW + s * 32);
; #pragma unroll
;       for (int ni = 0; ni < 2; ++ni) b[ni] = *(const bf16x8*)(S + boff + ni * 32 * LROW + s * 32);
;       *(u32x4*)(D + soff + s * 64 * LROW) = ra[s];
;       *(u32x4*)(D + T2 + soff + s * 64 * LROW) = rb[s];
;       ra[s] = *(const u32x4*)(an + s * astep + a_voff);
;       rb[s] = *(const u32x4*)(bn + s * bstep + b_voff);
; #pragma unroll
;       for (int mi = 0; mi < 4; ++mi)
; #pragma unroll
;         for (int ni = 0; ni < 2; ++ni) acc[mi][ni] = MFMA32(a[mi], b[ni], acc[mi][ni]);
;     }
;     __syncthreads();
;   }
	ds_read_b128 v[196:199], v194 offset:0
	ds_read_b128 v[212:215], v160 offset:0
	ds_read_b128 v[216:219], v160 offset:2048
	ds_read_b128 v[242:245], v160 offset:4096
	ds_read_b128 v[246:249], v160 offset:6144
	ds_read_b128 v[200:203], v194 offset:4096
	ds_read_b128 v[204:207], v194 offset:8192
	ds_read_b128 v[208:211], v194 offset:12288
	s_cmp_lt_u32 s56, s57
	s_cbranch_scc1 .Lg_gateup_loop
	s_waitcnt vmcnt(0) lgkmcnt(0)
	s_nop 7
	s_nop 7
	v_permlane16_swap_b32_e32 v114, v118
	v_permlane16_swap_b32_e32 v115, v119
	v_permlane16_swap_b32_e32 v116, v120
	v_permlane16_swap_b32_e32 v117, v121
	v_permlane16_swap_b32_e32 v122, v126
	v_permlane16_swap_b32_e32 v123, v127
	v_permlane16_swap_b32_e32 v124, v128
	v_permlane16_swap_b32_e32 v125, v129
	v_permlane16_swap_b32_e32 v98, v102
	v_permlane16_swap_b32_e32 v99, v103
	v_permlane16_swap_b32_e32 v100, v104
	v_permlane16_swap_b32_e32 v101, v105
	v_permlane16_swap_b32_e32 v106, v110
	v_permlane16_swap_b32_e32 v107, v111
	v_permlane16_swap_b32_e32 v108, v112
	v_permlane16_swap_b32_e32 v109, v113
	v_permlane16_swap_b32_e32 v82, v86
	v_permlane16_swap_b32_e32 v83, v87
	v_permlane16_swap_b32_e32 v84, v88
	v_permlane16_swap_b32_e32 v85, v89
	v_permlane16_swap_b32_e32 v90, v94
	v_permlane16_swap_b32_e32 v91, v95
	v_permlane16_swap_b32_e32 v92, v96
	v_permlane16_swap_b32_e32 v93, v97
	v_permlane16_swap_b32_e32 v66, v70
	v_permlane16_swap_b32_e32 v67, v71
	v_permlane16_swap_b32_e32 v68, v72
	v_permlane16_swap_b32_e32 v69, v73
	v_permlane16_swap_b32_e32 v74, v78
	v_permlane16_swap_b32_e32 v75, v79
	v_permlane16_swap_b32_e32 v76, v80
	v_permlane16_swap_b32_e32 v77, v81
	v_permlane16_swap_b32_e32 v50, v54
	v_permlane16_swap_b32_e32 v51, v55
	v_permlane16_swap_b32_e32 v52, v56
	v_permlane16_swap_b32_e32 v53, v57
	v_permlane16_swap_b32_e32 v58, v62
	v_permlane16_swap_b32_e32 v59, v63
	v_permlane16_swap_b32_e32 v60, v64
	v_permlane16_swap_b32_e32 v61, v65
	v_permlane16_swap_b32_e32 v34, v38
	v_permlane16_swap_b32_e32 v35, v39
	v_permlane16_swap_b32_e32 v36, v40
	v_permlane16_swap_b32_e32 v37, v41
	v_permlane16_swap_b32_e32 v42, v46
	v_permlane16_swap_b32_e32 v43, v47
	v_permlane16_swap_b32_e32 v44, v48
	v_permlane16_swap_b32_e32 v45, v49
	v_permlane16_swap_b32_e32 v18, v22
	v_permlane16_swap_b32_e32 v19, v23
	v_permlane16_swap_b32_e32 v20, v24
	v_permlane16_swap_b32_e32 v21, v25
	v_permlane16_swap_b32_e32 v26, v30
	v_permlane16_swap_b32_e32 v27, v31
	v_permlane16_swap_b32_e32 v28, v32
	v_permlane16_swap_b32_e32 v29, v33
	v_permlane16_swap_b32_e32 v2, v6
	v_permlane16_swap_b32_e32 v3, v7
	v_permlane16_swap_b32_e32 v4, v8
	v_permlane16_swap_b32_e32 v5, v9
	v_permlane16_swap_b32_e32 v10, v14
	v_permlane16_swap_b32_e32 v11, v15
	v_permlane16_swap_b32_e32 v12, v16
	v_permlane16_swap_b32_e32 v13, v17
	v_permlane32_swap_b32_e32 v114, v118
	v_permlane32_swap_b32_e32 v115, v119
	v_permlane32_swap_b32_e32 v116, v120
	v_permlane32_swap_b32_e32 v117, v121
	v_permlane32_swap_b32_e32 v122, v126
	v_permlane32_swap_b32_e32 v123, v127
	v_permlane32_swap_b32_e32 v124, v128
	v_permlane32_swap_b32_e32 v125, v129
	v_permlane32_swap_b32_e32 v98, v102
	v_permlane32_swap_b32_e32 v99, v103
	v_permlane32_swap_b32_e32 v100, v104
	v_permlane32_swap_b32_e32 v101, v105
	v_permlane32_swap_b32_e32 v106, v110
	v_permlane32_swap_b32_e32 v107, v111
	v_permlane32_swap_b32_e32 v108, v112
	v_permlane32_swap_b32_e32 v109, v113
	v_permlane32_swap_b32_e32 v82, v86
	v_permlane32_swap_b32_e32 v83, v87
	v_permlane32_swap_b32_e32 v84, v88
	v_permlane32_swap_b32_e32 v85, v89
	v_permlane32_swap_b32_e32 v90, v94
	v_permlane32_swap_b32_e32 v91, v95
	v_permlane32_swap_b32_e32 v92, v96
	v_permlane32_swap_b32_e32 v93, v97
	v_permlane32_swap_b32_e32 v66, v70
	v_permlane32_swap_b32_e32 v67, v71
	v_permlane32_swap_b32_e32 v68, v72
	v_permlane32_swap_b32_e32 v69, v73
	v_permlane32_swap_b32_e32 v74, v78
	v_permlane32_swap_b32_e32 v75, v79
	v_permlane32_swap_b32_e32 v76, v80
	v_permlane32_swap_b32_e32 v77, v81
	v_permlane32_swap_b32_e32 v50, v54
	v_permlane32_swap_b32_e32 v51, v55
	v_permlane32_swap_b32_e32 v52, v56
	v_permlane32_swap_b32_e32 v53, v57
	v_permlane32_swap_b32_e32 v58, v62
	v_permlane32_swap_b32_e32 v59, v63
	v_permlane32_swap_b32_e32 v60, v64
	v_permlane32_swap_b32_e32 v61, v65
	v_permlane32_swap_b32_e32 v34, v38
	v_permlane32_swap_b32_e32 v35, v39
	v_permlane32_swap_b32_e32 v36, v40
	v_permlane32_swap_b32_e32 v37, v41
	v_permlane32_swap_b32_e32 v42, v46
	v_permlane32_swap_b32_e32 v43, v47
	v_permlane32_swap_b32_e32 v44, v48
	v_permlane32_swap_b32_e32 v45, v49
	v_permlane32_swap_b32_e32 v18, v22
	v_permlane32_swap_b32_e32 v19, v23
	v_permlane32_swap_b32_e32 v20, v24
	v_permlane32_swap_b32_e32 v21, v25
	v_permlane32_swap_b32_e32 v26, v30
	v_permlane32_swap_b32_e32 v27, v31
	v_permlane32_swap_b32_e32 v28, v32
	v_permlane32_swap_b32_e32 v29, v33
	v_permlane32_swap_b32_e32 v2, v6
	v_permlane32_swap_b32_e32 v3, v7
	v_permlane32_swap_b32_e32 v4, v8
	v_permlane32_swap_b32_e32 v5, v9
	v_permlane32_swap_b32_e32 v10, v14
	v_permlane32_swap_b32_e32 v11, v15
	v_permlane32_swap_b32_e32 v12, v16
	v_permlane32_swap_b32_e32 v13, v17
	s_nop 1
	s_branch .LBB0_1568
